# hot loop heads (8 GEMM K loops, global attention tile loop) aligned to 64 bytes; on top of batched silu loads
# speedup vs baseline: 1.0095x; 1.0095x over previous
; #define PG8_STAGE(bufoff, gbase, voff) do { _Pragma("unroll") for (int _i = 0; _i < 2; ++_i) \
;     __builtin_amdgcn_global_load_lds((const unsigned*)((const char*)(gbase) + (voff)[_i]), (LAS unsigned*)(lds + (bufoff) + ldsw + _i * 8192), 16, 0, 0); } while (0)
; #define PG8_WAIT_V(n) asm volatile("s_waitcnt vmcnt(" #n ")" ::: "memory")
; #define PG8_BAR __builtin_amdgcn_s_barrier()
; template <class Epi, class Sched>
; DI void gemm_phase(LAS unsigned char* lds, const Gemm g, const Sched& S, const Epi& E) {
;     ...
;   f32x4 acc[2][2][4][2];
; #pragma unroll
;   for (int a = 0; a < 2; ++a)
; #pragma unroll
;     for (int b = 0; b < 2; ++b)
; #pragma unroll
;       for (int m = 0; m < 4; ++m)
; #pragma unroll
;         for (int n = 0; n < 2; ++n) acc[a][b][m][n] = (f32x4){0.f, 0.f, 0.f, 0.f};
;     ...
;   PG8_STAGE(PG8_SB(0, 0), cB, voffB); PG8_STAGE(PG8_SA(0, 0), cA, voffA); PG8_STAGE(PG8_SB(0, 1), cB + hstepB, voffB); PG8_STAGE(PG8_SA(0, 1), cA + hstep, voffA);
;   if (wr == 1) PG8_BAR;
;   PG8_WAIT_V(4); PG8_BAR;
;   PG8_STAGE(PG8_SB(1, 0), cB + kstep, voffB); PG8_STAGE(PG8_SA(1, 0), cA + kstep, voffA); PG8_STAGE(PG8_SB(1, 1), cB + hstepB + kstep, voffB);
;   PG8_WAIT_V(6); PG8_BAR;
.LBB0_135:
	v_lshl_add_u64 v[4:5], s[12:13], 0, v[0:1]
	v_mov_b32_e32 v131, v1
	v_lshl_add_u64 v[6:7], s[12:13], 0, v[130:131]
	v_and_b32_e32 v132, 15, v2
	v_bfe_u32 v136, v2, 4, 2
	s_add_i32 m0, s31, 0x18000
	v_lshl_add_u64 v[2:3], v[4:5], 0, s[70:71]
	v_lshl_add_u64 v[8:9], s[14:15], 0, v[0:1]
	s_waitcnt vmcnt(4)
	s_barrier
	global_load_lds_dwordx4 v[2:3], off
	v_lshl_add_u64 v[2:3], v[6:7], 0, s[70:71]
	s_add_i32 m0, s31, 0x1a000
	s_add_i32 s37, s31, 0x8000
	v_lshl_add_u64 v[10:11], s[14:15], 0, v[130:131]
	global_load_lds_dwordx4 v[2:3], off
	v_lshl_add_u64 v[2:3], v[8:9], 0, s[70:71]
	s_mov_b32 m0, s37
	s_add_i32 s38, s31, 0xa000
	v_lshl_add_u64 v[12:13], s[18:19], 0, v[0:1]
	global_load_lds_dwordx4 v[2:3], off
	v_lshl_add_u64 v[2:3], v[10:11], 0, s[70:71]
	s_mov_b32 m0, s38
	v_lshl_add_u64 v[14:15], s[18:19], 0, v[130:131]
	global_load_lds_dwordx4 v[2:3], off
	s_add_i32 m0, s31, 0x1c000
	v_lshl_add_u64 v[2:3], v[12:13], 0, s[70:71]
	global_load_lds_dwordx4 v[2:3], off
	v_lshl_add_u64 v[2:3], v[14:15], 0, s[70:71]
	s_add_i32 m0, s31, 0x1e000
	s_lshl_b32 s18, s21, 5
	global_load_lds_dwordx4 v[2:3], off
	s_waitcnt vmcnt(6)
	s_and_b32 s27, s18, 0x60
	v_mov_b32_e32 v129, 0
	v_lshl_or_b32 v148, s20, 6, v132
	s_cmp_lt_i32 s16, 64
	v_mov_b32_e32 v128, v129
	v_mov_b32_e32 v127, v129
	v_mov_b32_e32 v126, v129
	v_mov_b32_e32 v125, v129
	v_mov_b32_e32 v124, v129
	v_mov_b32_e32 v123, v129
	v_mov_b32_e32 v122, v129
	v_mov_b32_e32 v113, v129
	v_mov_b32_e32 v112, v129
	v_mov_b32_e32 v111, v129
	v_mov_b32_e32 v110, v129
	v_mov_b32_e32 v109, v129
	v_mov_b32_e32 v108, v129
	v_mov_b32_e32 v107, v129
	v_mov_b32_e32 v106, v129
	v_mov_b32_e32 v97, v129
	v_mov_b32_e32 v96, v129
	v_mov_b32_e32 v95, v129
	v_mov_b32_e32 v94, v129
	v_mov_b32_e32 v93, v129
	v_mov_b32_e32 v92, v129
	v_mov_b32_e32 v91, v129
	v_mov_b32_e32 v90, v129
	v_mov_b32_e32 v81, v129
	v_mov_b32_e32 v80, v129
	v_mov_b32_e32 v79, v129
	v_mov_b32_e32 v78, v129
	v_mov_b32_e32 v77, v129
	v_mov_b32_e32 v76, v129
	v_mov_b32_e32 v75, v129
	v_mov_b32_e32 v74, v129
	v_mov_b32_e32 v121, v129
	v_mov_b32_e32 v120, v129
	v_mov_b32_e32 v119, v129
	v_mov_b32_e32 v118, v129
	v_mov_b32_e32 v117, v129
	v_mov_b32_e32 v116, v129
	v_mov_b32_e32 v115, v129
	v_mov_b32_e32 v114, v129
	v_mov_b32_e32 v105, v129
	v_mov_b32_e32 v104, v129
	v_mov_b32_e32 v103, v129
	v_mov_b32_e32 v102, v129
	v_mov_b32_e32 v101, v129
	v_mov_b32_e32 v100, v129
	v_mov_b32_e32 v99, v129
	v_mov_b32_e32 v98, v129
	v_mov_b32_e32 v89, v129
	v_mov_b32_e32 v88, v129
	v_mov_b32_e32 v87, v129
	v_mov_b32_e32 v86, v129
	v_mov_b32_e32 v85, v129
	v_mov_b32_e32 v84, v129
	v_mov_b32_e32 v83, v129
	v_mov_b32_e32 v82, v129
	v_mov_b32_e32 v73, v129
	v_mov_b32_e32 v72, v129
	v_mov_b32_e32 v71, v129
	v_mov_b32_e32 v70, v129
	v_mov_b32_e32 v69, v129
	v_mov_b32_e32 v68, v129
	v_mov_b32_e32 v67, v129
	v_mov_b32_e32 v66, v129
	v_mov_b32_e32 v65, v129
	v_mov_b32_e32 v64, v129
	v_mov_b32_e32 v63, v129
	v_mov_b32_e32 v62, v129
	v_mov_b32_e32 v61, v129
	v_mov_b32_e32 v60, v129
	v_mov_b32_e32 v59, v129
	v_mov_b32_e32 v58, v129
	v_mov_b32_e32 v49, v129
	v_mov_b32_e32 v48, v129
	v_mov_b32_e32 v47, v129
	v_mov_b32_e32 v46, v129
	v_mov_b32_e32 v45, v129
	v_mov_b32_e32 v44, v129
	v_mov_b32_e32 v43, v129
	v_mov_b32_e32 v42, v129
	v_mov_b32_e32 v33, v129
	v_mov_b32_e32 v32, v129
	v_mov_b32_e32 v31, v129
	v_mov_b32_e32 v30, v129
	v_mov_b32_e32 v29, v129
	v_mov_b32_e32 v28, v129
	v_mov_b32_e32 v27, v129
	v_mov_b32_e32 v26, v129
	v_mov_b32_e32 v17, v129
	v_mov_b32_e32 v16, v129
	v_mov_b32_e32 v15, v129
	v_mov_b32_e32 v14, v129
	v_mov_b32_e32 v13, v129
	v_mov_b32_e32 v12, v129
	v_mov_b32_e32 v11, v129
	v_mov_b32_e32 v10, v129
	v_mov_b32_e32 v57, v129
	v_mov_b32_e32 v56, v129
	v_mov_b32_e32 v55, v129
	v_mov_b32_e32 v54, v129
	v_mov_b32_e32 v53, v129
	v_mov_b32_e32 v52, v129
	v_mov_b32_e32 v51, v129
	v_mov_b32_e32 v50, v129
	v_mov_b32_e32 v41, v129
	v_mov_b32_e32 v40, v129
	v_mov_b32_e32 v39, v129
	v_mov_b32_e32 v38, v129
	v_mov_b32_e32 v37, v129
	v_mov_b32_e32 v36, v129
	v_mov_b32_e32 v35, v129
	v_mov_b32_e32 v34, v129
	v_mov_b32_e32 v25, v129
	v_mov_b32_e32 v24, v129
	v_mov_b32_e32 v23, v129
	v_mov_b32_e32 v22, v129
	v_mov_b32_e32 v21, v129
	v_mov_b32_e32 v20, v129
	v_mov_b32_e32 v19, v129
	v_mov_b32_e32 v18, v129
	v_mov_b32_e32 v9, v129
	v_mov_b32_e32 v8, v129
	v_mov_b32_e32 v7, v129
	v_mov_b32_e32 v6, v129
	v_mov_b32_e32 v5, v129
	v_mov_b32_e32 v4, v129
	v_mov_b32_e32 v3, v129
	v_mov_b32_e32 v2, v129
	s_barrier
;   DI bool next(int i, Unit& o) const { if (i != 0 || !valid) return false; o = u; return true; }
; template <class Epi, class Sched>
; DI void gemm_phase(LAS unsigned char* lds, const Gemm g, const Sched& S, const Epi& E) {
;     ...
;     voffA[i] = (unsigned)(R * K + C) * 2u; voffB[i] = (unsigned)(Rb * K + C) * 2u;
;   }
;   const size_t kstep = (size_t)(BK * 2);
;   const size_t hstep = (size_t)HALF * K * 2;
;   const size_t hstepB = (Epi::BMAP == 2) ? (size_t)32 * K * 2 : hstep;
;   const size_t tstep = 2 * hstep;
;   const unsigned ldsw = (unsigned)wid * 1024u;
;   const int aoff = lds_byte(wr * 64 + fr, fq * 8), boff = lds_byte(wc * 32 + fr, fq * 8);
;     ...
;   Unit cur, nxt; int ui = 0;
;   if (!S.next(0, cur)) return;
;   f32x4 acc[2][2][4][2];
; #pragma unroll
;   for (int a = 0; a < 2; ++a)
; #pragma unroll
;     for (int b = 0; b < 2; ++b)
; #pragma unroll
;       for (int m = 0; m < 4; ++m)
; #pragma unroll
;         for (int n = 0; n < 2; ++n) acc[a][b][m][n] = (f32x4){0.f, 0.f, 0.f, 0.f};
	s_cbranch_scc1 .LBB0_138
	s_lshr_b32 s18, s17, 26
	s_add_i32 s18, s16, s18
	s_ashr_i32 s39, s18, 6
	v_lshlrev_b32_e32 v2, 4, v136
	v_lshlrev_b32_e32 v3, 6, v148
	s_movk_i32 s18, 0x3c0
	v_lshlrev_b32_e32 v4, 2, v148
	v_and_or_b32 v3, v3, s18, v2
	s_lshl_b32 s18, s20, 13
	v_and_b32_e32 v4, 32, v4
	v_bitop3_b32 v3, v3, s18, v4 bitop3:0xde
	v_lshlrev_b32_e32 v4, 2, v132
	v_lshl_or_b32 v2, v132, 6, v2
	s_lshl_b32 s18, s27, 7
	v_and_b32_e32 v4, 32, v4
	v_bitop3_b32 v137, v2, s18, v4 bitop3:0xde
	s_lshl_b64 s[18:19], s[0:1], 9
	s_or_b32 s1, s18, 0x100
	s_mul_i32 s17, s1, s17
	s_mul_hi_u32 s18, s1, s16
	s_add_i32 s17, s18, s17
	s_mul_i32 s18, s19, s16
	s_add_i32 s40, s39, -2
	s_add_i32 s17, s17, s18
	s_mul_i32 s1, s1, s16
	s_add_u32 s16, s60, s1
	s_addc_u32 s17, s61, s17
	v_mov_b32_e32 v2, 0
	v_lshl_add_u64 v[132:133], s[16:17], 0, v[0:1]
	v_lshl_add_u64 v[134:135], s[16:17], 0, v[130:131]
	s_mov_b32 s1, 0
	s_mov_b64 s[16:17], 0x80
	v_add_u32_e32 v138, 16, v3
	v_mov_b32_e32 v3, v2
	v_mov_b32_e32 v4, v2
	v_mov_b32_e32 v5, v2
	v_mov_b32_e32 v6, v2
	v_mov_b32_e32 v7, v2
	v_mov_b32_e32 v8, v2
	v_mov_b32_e32 v9, v2
	v_mov_b32_e32 v18, v2
	v_mov_b32_e32 v19, v2
	v_mov_b32_e32 v20, v2
	v_mov_b32_e32 v21, v2
	v_mov_b32_e32 v22, v2
	v_mov_b32_e32 v23, v2
	v_mov_b32_e32 v24, v2
	v_mov_b32_e32 v25, v2
	v_mov_b32_e32 v34, v2
	v_mov_b32_e32 v35, v2
	v_mov_b32_e32 v36, v2
	v_mov_b32_e32 v37, v2
	v_mov_b32_e32 v38, v2
	v_mov_b32_e32 v39, v2
	v_mov_b32_e32 v40, v2
	v_mov_b32_e32 v41, v2
	v_mov_b32_e32 v50, v2
	v_mov_b32_e32 v51, v2
	v_mov_b32_e32 v52, v2
	v_mov_b32_e32 v53, v2
	v_mov_b32_e32 v54, v2
	v_mov_b32_e32 v55, v2
	v_mov_b32_e32 v56, v2
	v_mov_b32_e32 v57, v2
	v_mov_b32_e32 v10, v2
	v_mov_b32_e32 v11, v2
	v_mov_b32_e32 v12, v2
	v_mov_b32_e32 v13, v2
	v_mov_b32_e32 v14, v2
	v_mov_b32_e32 v15, v2
	v_mov_b32_e32 v16, v2
	v_mov_b32_e32 v17, v2
	v_mov_b32_e32 v26, v2
	v_mov_b32_e32 v27, v2
	v_mov_b32_e32 v28, v2
	v_mov_b32_e32 v29, v2
	v_mov_b32_e32 v30, v2
	v_mov_b32_e32 v31, v2
	v_mov_b32_e32 v32, v2
	v_mov_b32_e32 v33, v2
	v_mov_b32_e32 v42, v2
	v_mov_b32_e32 v43, v2
	v_mov_b32_e32 v44, v2
	v_mov_b32_e32 v45, v2
	v_mov_b32_e32 v46, v2
	v_mov_b32_e32 v47, v2
	v_mov_b32_e32 v48, v2
	v_mov_b32_e32 v49, v2
	v_mov_b32_e32 v58, v2
	v_mov_b32_e32 v59, v2
	v_mov_b32_e32 v60, v2
	v_mov_b32_e32 v61, v2
	v_mov_b32_e32 v62, v2
	v_mov_b32_e32 v63, v2
	v_mov_b32_e32 v64, v2
	v_mov_b32_e32 v65, v2
	v_mov_b32_e32 v66, v2
	v_mov_b32_e32 v67, v2
	v_mov_b32_e32 v68, v2
	v_mov_b32_e32 v69, v2
	v_mov_b32_e32 v70, v2
	v_mov_b32_e32 v71, v2
	v_mov_b32_e32 v72, v2
	v_mov_b32_e32 v73, v2
	v_mov_b32_e32 v82, v2
	v_mov_b32_e32 v83, v2
	v_mov_b32_e32 v84, v2
	v_mov_b32_e32 v85, v2
	v_mov_b32_e32 v86, v2
	v_mov_b32_e32 v87, v2
	v_mov_b32_e32 v88, v2
	v_mov_b32_e32 v89, v2
	v_mov_b32_e32 v98, v2
	v_mov_b32_e32 v99, v2
	v_mov_b32_e32 v100, v2
	v_mov_b32_e32 v101, v2
	v_mov_b32_e32 v102, v2
	v_mov_b32_e32 v103, v2
	v_mov_b32_e32 v104, v2
	v_mov_b32_e32 v105, v2
	v_mov_b32_e32 v114, v2
	v_mov_b32_e32 v115, v2
	v_mov_b32_e32 v116, v2
	v_mov_b32_e32 v117, v2
	v_mov_b32_e32 v118, v2
	v_mov_b32_e32 v119, v2
	v_mov_b32_e32 v120, v2
	v_mov_b32_e32 v121, v2
	v_mov_b32_e32 v74, v2
	v_mov_b32_e32 v75, v2
	v_mov_b32_e32 v76, v2
	v_mov_b32_e32 v77, v2
	v_mov_b32_e32 v78, v2
	v_mov_b32_e32 v79, v2
	v_mov_b32_e32 v80, v2
	v_mov_b32_e32 v81, v2
	v_mov_b32_e32 v90, v2
	v_mov_b32_e32 v91, v2
	v_mov_b32_e32 v92, v2
	v_mov_b32_e32 v93, v2
	v_mov_b32_e32 v94, v2
	v_mov_b32_e32 v95, v2
	v_mov_b32_e32 v96, v2
	v_mov_b32_e32 v97, v2
	v_mov_b32_e32 v106, v2
	v_mov_b32_e32 v107, v2
	v_mov_b32_e32 v108, v2
	v_mov_b32_e32 v109, v2
	v_mov_b32_e32 v110, v2
	v_mov_b32_e32 v111, v2
	v_mov_b32_e32 v112, v2
	v_mov_b32_e32 v113, v2
	v_mov_b32_e32 v122, v2
	v_mov_b32_e32 v123, v2
	v_mov_b32_e32 v124, v2
	v_mov_b32_e32 v125, v2
	v_mov_b32_e32 v126, v2
	v_mov_b32_e32 v127, v2
	v_mov_b32_e32 v128, v2
	v_mov_b32_e32 v129, v2
	.p2align	6

; #define PG8_STAGE(bufoff, gbase, voff) do { _Pragma("unroll") for (int _i = 0; _i < 2; ++_i) \
;     __builtin_amdgcn_global_load_lds((const unsigned*)((const char*)(gbase) + (voff)[_i]), (LAS unsigned*)(lds + (bufoff) + ldsw + _i * 8192), 16, 0, 0); } while (0)
; #define PG8_WAIT_V(n) asm volatile("s_waitcnt vmcnt(" #n ")" ::: "memory")
; #define PG8_BAR __builtin_amdgcn_s_barrier()
; template <class Epi, class Sched>
; DI void gemm_phase(LAS unsigned char* lds, const Gemm g, const Sched& S, const Epi& E) {
;     ...
;   f32x4 acc[2][2][4][2];
; #pragma unroll
;   for (int a = 0; a < 2; ++a)
; #pragma unroll
;     for (int b = 0; b < 2; ++b)
; #pragma unroll
;       for (int m = 0; m < 4; ++m)
; #pragma unroll
;         for (int n = 0; n < 2; ++n) acc[a][b][m][n] = (f32x4){0.f, 0.f, 0.f, 0.f};
;     ...
;   PG8_STAGE(PG8_SB(0, 0), cB, voffB); PG8_STAGE(PG8_SA(0, 0), cA, voffA); PG8_STAGE(PG8_SB(0, 1), cB + hstepB, voffB); PG8_STAGE(PG8_SA(0, 1), cA + hstep, voffA);
;   if (wr == 1) PG8_BAR;
;   PG8_WAIT_V(4); PG8_BAR;
;   PG8_STAGE(PG8_SB(1, 0), cB + kstep, voffB); PG8_STAGE(PG8_SA(1, 0), cA + kstep, voffA); PG8_STAGE(PG8_SB(1, 1), cB + hstepB + kstep, voffB);
;   PG8_WAIT_V(6); PG8_BAR;
.LBB0_151:
	v_lshl_add_u64 v[4:5], s[2:3], 0, v[0:1]
	v_mov_b32_e32 v131, v1
	v_lshl_add_u64 v[6:7], s[2:3], 0, v[130:131]
	v_and_b32_e32 v132, 15, v2
	v_bfe_u32 v136, v2, 4, 2
	s_add_i32 m0, s24, 0x18000
	v_lshl_add_u64 v[2:3], v[4:5], 0, s[70:71]
	v_lshl_add_u64 v[8:9], s[12:13], 0, v[0:1]
	s_waitcnt vmcnt(4)
	s_barrier
	global_load_lds_dwordx4 v[2:3], off
	v_lshl_add_u64 v[2:3], v[6:7], 0, s[70:71]
	s_add_i32 m0, s24, 0x1a000
	s_add_i32 s30, s24, 0x8000
	v_lshl_add_u64 v[10:11], s[12:13], 0, v[130:131]
	global_load_lds_dwordx4 v[2:3], off
	v_lshl_add_u64 v[2:3], v[8:9], 0, s[70:71]
	s_mov_b32 m0, s30
	s_add_i32 s31, s24, 0xa000
	v_lshl_add_u64 v[12:13], s[16:17], 0, v[0:1]
	global_load_lds_dwordx4 v[2:3], off
	v_lshl_add_u64 v[2:3], v[10:11], 0, s[70:71]
	s_mov_b32 m0, s31
	v_lshl_add_u64 v[14:15], s[16:17], 0, v[130:131]
	global_load_lds_dwordx4 v[2:3], off
	s_add_i32 m0, s24, 0x1c000
	v_lshl_add_u64 v[2:3], v[12:13], 0, s[70:71]
	global_load_lds_dwordx4 v[2:3], off
	v_lshl_add_u64 v[2:3], v[14:15], 0, s[70:71]
	s_add_i32 m0, s24, 0x1e000
	s_lshl_b32 s16, s19, 5
	global_load_lds_dwordx4 v[2:3], off
	s_waitcnt vmcnt(6)
	s_and_b32 s22, s16, 0x60
	v_mov_b32_e32 v129, 0
	v_lshl_or_b32 v148, s18, 6, v132
	s_cmp_lt_i32 s14, 64
	v_mov_b32_e32 v128, v129
	v_mov_b32_e32 v127, v129
	v_mov_b32_e32 v126, v129
	v_mov_b32_e32 v125, v129
	v_mov_b32_e32 v124, v129
	v_mov_b32_e32 v123, v129
	v_mov_b32_e32 v122, v129
	v_mov_b32_e32 v113, v129
	v_mov_b32_e32 v112, v129
	v_mov_b32_e32 v111, v129
	v_mov_b32_e32 v110, v129
	v_mov_b32_e32 v109, v129
	v_mov_b32_e32 v108, v129
	v_mov_b32_e32 v107, v129
	v_mov_b32_e32 v106, v129
	v_mov_b32_e32 v97, v129
	v_mov_b32_e32 v96, v129
	v_mov_b32_e32 v95, v129
	v_mov_b32_e32 v94, v129
	v_mov_b32_e32 v93, v129
	v_mov_b32_e32 v92, v129
	v_mov_b32_e32 v91, v129
	v_mov_b32_e32 v90, v129
	v_mov_b32_e32 v81, v129
	v_mov_b32_e32 v80, v129
	v_mov_b32_e32 v79, v129
	v_mov_b32_e32 v78, v129
	v_mov_b32_e32 v77, v129
	v_mov_b32_e32 v76, v129
	v_mov_b32_e32 v75, v129
	v_mov_b32_e32 v74, v129
	v_mov_b32_e32 v121, v129
	v_mov_b32_e32 v120, v129
	v_mov_b32_e32 v119, v129
	v_mov_b32_e32 v118, v129
	v_mov_b32_e32 v117, v129
	v_mov_b32_e32 v116, v129
	v_mov_b32_e32 v115, v129
	v_mov_b32_e32 v114, v129
	v_mov_b32_e32 v105, v129
	v_mov_b32_e32 v104, v129
	v_mov_b32_e32 v103, v129
	v_mov_b32_e32 v102, v129
	v_mov_b32_e32 v101, v129
	v_mov_b32_e32 v100, v129
	v_mov_b32_e32 v99, v129
	v_mov_b32_e32 v98, v129
	v_mov_b32_e32 v89, v129
	v_mov_b32_e32 v88, v129
	v_mov_b32_e32 v87, v129
	v_mov_b32_e32 v86, v129
	v_mov_b32_e32 v85, v129
	v_mov_b32_e32 v84, v129
	v_mov_b32_e32 v83, v129
	v_mov_b32_e32 v82, v129
	v_mov_b32_e32 v73, v129
	v_mov_b32_e32 v72, v129
	v_mov_b32_e32 v71, v129
	v_mov_b32_e32 v70, v129
	v_mov_b32_e32 v69, v129
	v_mov_b32_e32 v68, v129
	v_mov_b32_e32 v67, v129
	v_mov_b32_e32 v66, v129
	v_mov_b32_e32 v65, v129
	v_mov_b32_e32 v64, v129
	v_mov_b32_e32 v63, v129
	v_mov_b32_e32 v62, v129
	v_mov_b32_e32 v61, v129
	v_mov_b32_e32 v60, v129
	v_mov_b32_e32 v59, v129
	v_mov_b32_e32 v58, v129
	v_mov_b32_e32 v49, v129
	v_mov_b32_e32 v48, v129
	v_mov_b32_e32 v47, v129
	v_mov_b32_e32 v46, v129
	v_mov_b32_e32 v45, v129
	v_mov_b32_e32 v44, v129
	v_mov_b32_e32 v43, v129
	v_mov_b32_e32 v42, v129
	v_mov_b32_e32 v33, v129
	v_mov_b32_e32 v32, v129
	v_mov_b32_e32 v31, v129
	v_mov_b32_e32 v30, v129
	v_mov_b32_e32 v29, v129
	v_mov_b32_e32 v28, v129
	v_mov_b32_e32 v27, v129
	v_mov_b32_e32 v26, v129
	v_mov_b32_e32 v17, v129
	v_mov_b32_e32 v16, v129
	v_mov_b32_e32 v15, v129
	v_mov_b32_e32 v14, v129
	v_mov_b32_e32 v13, v129
	v_mov_b32_e32 v12, v129
	v_mov_b32_e32 v11, v129
	v_mov_b32_e32 v10, v129
	v_mov_b32_e32 v57, v129
	v_mov_b32_e32 v56, v129
	v_mov_b32_e32 v55, v129
	v_mov_b32_e32 v54, v129
	v_mov_b32_e32 v53, v129
	v_mov_b32_e32 v52, v129
	v_mov_b32_e32 v51, v129
	v_mov_b32_e32 v50, v129
	v_mov_b32_e32 v41, v129
	v_mov_b32_e32 v40, v129
	v_mov_b32_e32 v39, v129
	v_mov_b32_e32 v38, v129
	v_mov_b32_e32 v37, v129
	v_mov_b32_e32 v36, v129
	v_mov_b32_e32 v35, v129
	v_mov_b32_e32 v34, v129
	v_mov_b32_e32 v25, v129
	v_mov_b32_e32 v24, v129
	v_mov_b32_e32 v23, v129
	v_mov_b32_e32 v22, v129
	v_mov_b32_e32 v21, v129
	v_mov_b32_e32 v20, v129
	v_mov_b32_e32 v19, v129
	v_mov_b32_e32 v18, v129
	v_mov_b32_e32 v9, v129
	v_mov_b32_e32 v8, v129
	v_mov_b32_e32 v7, v129
	v_mov_b32_e32 v6, v129
	v_mov_b32_e32 v5, v129
	v_mov_b32_e32 v4, v129
	v_mov_b32_e32 v3, v129
	v_mov_b32_e32 v2, v129
	s_barrier
;   DI bool next(int i, Unit& o) const { if (i != 0 || !valid) return false; o = u; return true; }
; template <class Epi, class Sched>
; DI void gemm_phase(LAS unsigned char* lds, const Gemm g, const Sched& S, const Epi& E) {
;     ...
;     voffA[i] = (unsigned)(R * K + C) * 2u; voffB[i] = (unsigned)(Rb * K + C) * 2u;
;   }
;   const size_t kstep = (size_t)(BK * 2);
;   const size_t hstep = (size_t)HALF * K * 2;
;   const size_t hstepB = (Epi::BMAP == 2) ? (size_t)32 * K * 2 : hstep;
;   const size_t tstep = 2 * hstep;
;   const unsigned ldsw = (unsigned)wid * 1024u;
;   const int aoff = lds_byte(wr * 64 + fr, fq * 8), boff = lds_byte(wc * 32 + fr, fq * 8);
;     ...
;   Unit cur, nxt; int ui = 0;
;   if (!S.next(0, cur)) return;
;   f32x4 acc[2][2][4][2];
; #pragma unroll
;   for (int a = 0; a < 2; ++a)
; #pragma unroll
;     for (int b = 0; b < 2; ++b)
; #pragma unroll
;       for (int m = 0; m < 4; ++m)
; #pragma unroll
;         for (int n = 0; n < 2; ++n) acc[a][b][m][n] = (f32x4){0.f, 0.f, 0.f, 0.f};
	s_cbranch_scc1 .LBB0_154
	s_lshr_b32 s15, s15, 26
	s_add_i32 s15, s14, s15
	s_ashr_i32 s34, s15, 6
	v_lshlrev_b32_e32 v2, 4, v136
	v_lshlrev_b32_e32 v3, 6, v148
	s_movk_i32 s15, 0x3c0
	v_lshlrev_b32_e32 v4, 2, v148
	v_and_or_b32 v3, v3, s15, v2
	s_lshl_b32 s15, s18, 13
	v_and_b32_e32 v4, 32, v4
	v_bitop3_b32 v3, v3, s15, v4 bitop3:0xde
	v_lshlrev_b32_e32 v4, 2, v132
	v_lshl_or_b32 v2, v132, 6, v2
	s_lshl_b32 s15, s22, 7
	v_and_b32_e32 v4, 32, v4
	v_readlane_b32 s16, v253, 33
	s_add_i32 s35, s34, -2
	v_bitop3_b32 v137, v2, s15, v4 bitop3:0xde
	s_mul_hi_i32 s15, s16, s14
	s_mul_i32 s14, s16, s14
	s_add_u32 s14, s60, s14
	s_addc_u32 s15, s61, s15
	v_mov_b32_e32 v2, 0
	v_lshl_add_u64 v[132:133], s[14:15], 0, v[0:1]
	v_lshl_add_u64 v[134:135], s[14:15], 0, v[130:131]
	s_mov_b32 s16, 0
	s_mov_b64 s[14:15], 0x5800080
	v_add_u32_e32 v138, 16, v3
	v_mov_b32_e32 v3, v2
	v_mov_b32_e32 v4, v2
	v_mov_b32_e32 v5, v2
	v_mov_b32_e32 v6, v2
	v_mov_b32_e32 v7, v2
	v_mov_b32_e32 v8, v2
	v_mov_b32_e32 v9, v2
	v_mov_b32_e32 v18, v2
	v_mov_b32_e32 v19, v2
	v_mov_b32_e32 v20, v2
	v_mov_b32_e32 v21, v2
	v_mov_b32_e32 v22, v2
	v_mov_b32_e32 v23, v2
	v_mov_b32_e32 v24, v2
	v_mov_b32_e32 v25, v2
	v_mov_b32_e32 v34, v2
	v_mov_b32_e32 v35, v2
	v_mov_b32_e32 v36, v2
	v_mov_b32_e32 v37, v2
	v_mov_b32_e32 v38, v2
	v_mov_b32_e32 v39, v2
	v_mov_b32_e32 v40, v2
	v_mov_b32_e32 v41, v2
	v_mov_b32_e32 v50, v2
	v_mov_b32_e32 v51, v2
	v_mov_b32_e32 v52, v2
	v_mov_b32_e32 v53, v2
	v_mov_b32_e32 v54, v2
	v_mov_b32_e32 v55, v2
	v_mov_b32_e32 v56, v2
	v_mov_b32_e32 v57, v2
	v_mov_b32_e32 v10, v2
	v_mov_b32_e32 v11, v2
	v_mov_b32_e32 v12, v2
	v_mov_b32_e32 v13, v2
	v_mov_b32_e32 v14, v2
	v_mov_b32_e32 v15, v2
	v_mov_b32_e32 v16, v2
	v_mov_b32_e32 v17, v2
	v_mov_b32_e32 v26, v2
	v_mov_b32_e32 v27, v2
	v_mov_b32_e32 v28, v2
	v_mov_b32_e32 v29, v2
	v_mov_b32_e32 v30, v2
	v_mov_b32_e32 v31, v2
	v_mov_b32_e32 v32, v2
	v_mov_b32_e32 v33, v2
	v_mov_b32_e32 v42, v2
	v_mov_b32_e32 v43, v2
	v_mov_b32_e32 v44, v2
	v_mov_b32_e32 v45, v2
	v_mov_b32_e32 v46, v2
	v_mov_b32_e32 v47, v2
	v_mov_b32_e32 v48, v2
	v_mov_b32_e32 v49, v2
	v_mov_b32_e32 v58, v2
	v_mov_b32_e32 v59, v2
	v_mov_b32_e32 v60, v2
	v_mov_b32_e32 v61, v2
	v_mov_b32_e32 v62, v2
	v_mov_b32_e32 v63, v2
	v_mov_b32_e32 v64, v2
	v_mov_b32_e32 v65, v2
	v_mov_b32_e32 v66, v2
	v_mov_b32_e32 v67, v2
	v_mov_b32_e32 v68, v2
	v_mov_b32_e32 v69, v2
	v_mov_b32_e32 v70, v2
	v_mov_b32_e32 v71, v2
	v_mov_b32_e32 v72, v2
	v_mov_b32_e32 v73, v2
	v_mov_b32_e32 v82, v2
	v_mov_b32_e32 v83, v2
	v_mov_b32_e32 v84, v2
	v_mov_b32_e32 v85, v2
	v_mov_b32_e32 v86, v2
	v_mov_b32_e32 v87, v2
	v_mov_b32_e32 v88, v2
	v_mov_b32_e32 v89, v2
	v_mov_b32_e32 v98, v2
	v_mov_b32_e32 v99, v2
	v_mov_b32_e32 v100, v2
	v_mov_b32_e32 v101, v2
	v_mov_b32_e32 v102, v2
	v_mov_b32_e32 v103, v2
	v_mov_b32_e32 v104, v2
	v_mov_b32_e32 v105, v2
	v_mov_b32_e32 v114, v2
	v_mov_b32_e32 v115, v2
	v_mov_b32_e32 v116, v2
	v_mov_b32_e32 v117, v2
	v_mov_b32_e32 v118, v2
	v_mov_b32_e32 v119, v2
	v_mov_b32_e32 v120, v2
	v_mov_b32_e32 v121, v2
	v_mov_b32_e32 v74, v2
	v_mov_b32_e32 v75, v2
	v_mov_b32_e32 v76, v2
	v_mov_b32_e32 v77, v2
	v_mov_b32_e32 v78, v2
	v_mov_b32_e32 v79, v2
	v_mov_b32_e32 v80, v2
	v_mov_b32_e32 v81, v2
	v_mov_b32_e32 v90, v2
	v_mov_b32_e32 v91, v2
	v_mov_b32_e32 v92, v2
	v_mov_b32_e32 v93, v2
	v_mov_b32_e32 v94, v2
	v_mov_b32_e32 v95, v2
	v_mov_b32_e32 v96, v2
	v_mov_b32_e32 v97, v2
	v_mov_b32_e32 v106, v2
	v_mov_b32_e32 v107, v2
	v_mov_b32_e32 v108, v2
	v_mov_b32_e32 v109, v2
	v_mov_b32_e32 v110, v2
	v_mov_b32_e32 v111, v2
	v_mov_b32_e32 v112, v2
	v_mov_b32_e32 v113, v2
	v_mov_b32_e32 v122, v2
	v_mov_b32_e32 v123, v2
	v_mov_b32_e32 v124, v2
	v_mov_b32_e32 v125, v2
	v_mov_b32_e32 v126, v2
	v_mov_b32_e32 v127, v2
	v_mov_b32_e32 v128, v2
	v_mov_b32_e32 v129, v2
	.p2align	6

;   DI bool next(int i, Unit& o) const { if (i != 0 || !valid) return false; o = u; return true; }
; template <class Epi, class Sched>
; DI void gemm_phase(LAS unsigned char* lds, const Gemm g, const Sched& S, const Epi& E) {
;     ...
;   for (;;) {
;     const bool has_next = S.next(ui + 1, nxt);
;     const char* nA = has_next ? (const char*)g.A + (size_t)nxt.pm * tstep : cA; const char* nB = has_next ? (const char*)g.Bt + (size_t)nxt.pn * tstep : cB;
;     for (int t = 0; t < nt; t += 2) {
;     ...
;     E(acc, cur, wr, wc, fr, fq);
;     if (!has_next) break;
; #pragma unroll
;     for (int a = 0; a < 2; ++a)
; #pragma unroll
;       for (int b = 0; b < 2; ++b)
; #pragma unroll
;         for (int m = 0; m < 4; ++m)
; #pragma unroll
;           for (int n = 0; n < 2; ++n) acc[a][b][m][n] = (f32x4){0.f, 0.f, 0.f, 0.f};
;     cur = nxt; cA = nA; cB = nB; ++ui;
.LBB0_176:
	s_waitcnt vmcnt(8)
	v_mov_b32_e32 v125, 0
	s_andn2_b64 vcc, exec, s[16:17]
	v_mov_b32_e32 v124, v125
	v_mov_b32_e32 v123, v125
	v_mov_b32_e32 v122, v125
	v_mov_b32_e32 v121, v125
	v_mov_b32_e32 v120, v125
	v_mov_b32_e32 v119, v125
	v_mov_b32_e32 v118, v125
	v_mov_b32_e32 v113, v125
	v_mov_b32_e32 v112, v125
	v_mov_b32_e32 v111, v125
	v_mov_b32_e32 v110, v125
	v_mov_b32_e32 v105, v125
	v_mov_b32_e32 v104, v125
	v_mov_b32_e32 v103, v125
	v_mov_b32_e32 v102, v125
	v_mov_b32_e32 v97, v125
	v_mov_b32_e32 v96, v125
	v_mov_b32_e32 v95, v125
	v_mov_b32_e32 v94, v125
	v_mov_b32_e32 v89, v125
	v_mov_b32_e32 v88, v125
	v_mov_b32_e32 v87, v125
	v_mov_b32_e32 v86, v125
	v_mov_b32_e32 v81, v125
	v_mov_b32_e32 v80, v125
	v_mov_b32_e32 v79, v125
	v_mov_b32_e32 v78, v125
	v_mov_b32_e32 v73, v125
	v_mov_b32_e32 v72, v125
	v_mov_b32_e32 v71, v125
	v_mov_b32_e32 v70, v125
	v_mov_b32_e32 v129, v125
	v_mov_b32_e32 v128, v125
	v_mov_b32_e32 v127, v125
	v_mov_b32_e32 v126, v125
	v_mov_b32_e32 v117, v125
	v_mov_b32_e32 v116, v125
	v_mov_b32_e32 v115, v125
	v_mov_b32_e32 v114, v125
	v_mov_b32_e32 v109, v125
	v_mov_b32_e32 v108, v125
	v_mov_b32_e32 v107, v125
	v_mov_b32_e32 v106, v125
	v_mov_b32_e32 v101, v125
	v_mov_b32_e32 v100, v125
	v_mov_b32_e32 v99, v125
	v_mov_b32_e32 v98, v125
	v_mov_b32_e32 v93, v125
	v_mov_b32_e32 v92, v125
	v_mov_b32_e32 v91, v125
	v_mov_b32_e32 v90, v125
	v_mov_b32_e32 v85, v125
	v_mov_b32_e32 v84, v125
	v_mov_b32_e32 v83, v125
	v_mov_b32_e32 v82, v125
	v_mov_b32_e32 v77, v125
	v_mov_b32_e32 v76, v125
	v_mov_b32_e32 v75, v125
	v_mov_b32_e32 v74, v125
	v_mov_b32_e32 v69, v125
	v_mov_b32_e32 v68, v125
	v_mov_b32_e32 v67, v125
	v_mov_b32_e32 v66, v125
	v_mov_b32_e32 v65, v125
	v_mov_b32_e32 v64, v125
	v_mov_b32_e32 v63, v125
	v_mov_b32_e32 v62, v125
	v_mov_b32_e32 v57, v125
	v_mov_b32_e32 v56, v125
	v_mov_b32_e32 v55, v125
	v_mov_b32_e32 v54, v125
	v_mov_b32_e32 v49, v125
	v_mov_b32_e32 v48, v125
	v_mov_b32_e32 v47, v125
	v_mov_b32_e32 v46, v125
	v_mov_b32_e32 v41, v125
	v_mov_b32_e32 v40, v125
	v_mov_b32_e32 v39, v125
	v_mov_b32_e32 v38, v125
	v_mov_b32_e32 v33, v125
	v_mov_b32_e32 v32, v125
	v_mov_b32_e32 v31, v125
	v_mov_b32_e32 v30, v125
	v_mov_b32_e32 v25, v125
	v_mov_b32_e32 v24, v125
	v_mov_b32_e32 v23, v125
	v_mov_b32_e32 v22, v125
	v_mov_b32_e32 v17, v125
	v_mov_b32_e32 v16, v125
	v_mov_b32_e32 v15, v125
	v_mov_b32_e32 v14, v125
	v_mov_b32_e32 v9, v125
	v_mov_b32_e32 v8, v125
	v_mov_b32_e32 v7, v125
	v_mov_b32_e32 v6, v125
	v_mov_b32_e32 v61, v125
	v_mov_b32_e32 v60, v125
	v_mov_b32_e32 v59, v125
	v_mov_b32_e32 v58, v125
	v_mov_b32_e32 v53, v125
	v_mov_b32_e32 v52, v125
	v_mov_b32_e32 v51, v125
	v_mov_b32_e32 v50, v125
	v_mov_b32_e32 v45, v125
	v_mov_b32_e32 v44, v125
	v_mov_b32_e32 v43, v125
	v_mov_b32_e32 v42, v125
	v_mov_b32_e32 v37, v125
	v_mov_b32_e32 v36, v125
	v_mov_b32_e32 v35, v125
	v_mov_b32_e32 v34, v125
	v_mov_b32_e32 v29, v125
	v_mov_b32_e32 v28, v125
	v_mov_b32_e32 v27, v125
	v_mov_b32_e32 v26, v125
	v_mov_b32_e32 v21, v125
	v_mov_b32_e32 v20, v125
	v_mov_b32_e32 v19, v125
	v_mov_b32_e32 v18, v125
	v_mov_b32_e32 v13, v125
	v_mov_b32_e32 v12, v125
	v_mov_b32_e32 v11, v125
	v_mov_b32_e32 v10, v125
	v_mov_b32_e32 v5, v125
	v_mov_b32_e32 v4, v125
	v_mov_b32_e32 v3, v125
	v_mov_b32_e32 v2, v125
	s_cbranch_vccnz .LBB0_162
	s_add_u32 s22, s22, 0x80
	s_addc_u32 s23, s23, 0
	s_add_u32 s49, s24, 0x100
	v_mov_b32_e32 v2, 0
	s_addc_u32 s50, s25, 0
	s_mov_b32 s24, 0
	v_mov_b32_e32 v3, v2
	v_mov_b32_e32 v4, v2
	v_mov_b32_e32 v5, v2
	v_mov_b32_e32 v10, v2
	v_mov_b32_e32 v11, v2
	v_mov_b32_e32 v12, v2
	v_mov_b32_e32 v13, v2
	v_mov_b32_e32 v18, v2
	v_mov_b32_e32 v19, v2
	v_mov_b32_e32 v20, v2
	v_mov_b32_e32 v21, v2
	v_mov_b32_e32 v26, v2
	v_mov_b32_e32 v27, v2
	v_mov_b32_e32 v28, v2
	v_mov_b32_e32 v29, v2
	v_mov_b32_e32 v34, v2
	v_mov_b32_e32 v35, v2
	v_mov_b32_e32 v36, v2
	v_mov_b32_e32 v37, v2
	v_mov_b32_e32 v42, v2
	v_mov_b32_e32 v43, v2
	v_mov_b32_e32 v44, v2
	v_mov_b32_e32 v45, v2
	v_mov_b32_e32 v50, v2
	v_mov_b32_e32 v51, v2
	v_mov_b32_e32 v52, v2
	v_mov_b32_e32 v53, v2
	v_mov_b32_e32 v58, v2
	v_mov_b32_e32 v59, v2
	v_mov_b32_e32 v60, v2
	v_mov_b32_e32 v61, v2
	v_mov_b32_e32 v6, v2
	v_mov_b32_e32 v7, v2
	v_mov_b32_e32 v8, v2
	v_mov_b32_e32 v9, v2
	v_mov_b32_e32 v14, v2
	v_mov_b32_e32 v15, v2
	v_mov_b32_e32 v16, v2
	v_mov_b32_e32 v17, v2
	v_mov_b32_e32 v22, v2
	v_mov_b32_e32 v23, v2
	v_mov_b32_e32 v24, v2
	v_mov_b32_e32 v25, v2
	v_mov_b32_e32 v30, v2
	v_mov_b32_e32 v31, v2
	v_mov_b32_e32 v32, v2
	v_mov_b32_e32 v33, v2
	v_mov_b32_e32 v38, v2
	v_mov_b32_e32 v39, v2
	v_mov_b32_e32 v40, v2
	v_mov_b32_e32 v41, v2
	v_mov_b32_e32 v46, v2
	v_mov_b32_e32 v47, v2
	v_mov_b32_e32 v48, v2
	v_mov_b32_e32 v49, v2
	v_mov_b32_e32 v54, v2
	v_mov_b32_e32 v55, v2
	v_mov_b32_e32 v56, v2
	v_mov_b32_e32 v57, v2
	v_mov_b32_e32 v62, v2
	v_mov_b32_e32 v63, v2
	v_mov_b32_e32 v64, v2
	v_mov_b32_e32 v65, v2
	v_mov_b32_e32 v66, v2
	v_mov_b32_e32 v67, v2
	v_mov_b32_e32 v68, v2
	v_mov_b32_e32 v69, v2
	v_mov_b32_e32 v74, v2
	v_mov_b32_e32 v75, v2
	v_mov_b32_e32 v76, v2
	v_mov_b32_e32 v77, v2
	v_mov_b32_e32 v82, v2
	v_mov_b32_e32 v83, v2
	v_mov_b32_e32 v84, v2
	v_mov_b32_e32 v85, v2
	v_mov_b32_e32 v90, v2
	v_mov_b32_e32 v91, v2
	v_mov_b32_e32 v92, v2
	v_mov_b32_e32 v93, v2
	v_mov_b32_e32 v98, v2
	v_mov_b32_e32 v99, v2
	v_mov_b32_e32 v100, v2
	v_mov_b32_e32 v101, v2
	v_mov_b32_e32 v106, v2
	v_mov_b32_e32 v107, v2
	v_mov_b32_e32 v108, v2
	v_mov_b32_e32 v109, v2
	v_mov_b32_e32 v114, v2
	v_mov_b32_e32 v115, v2
	v_mov_b32_e32 v116, v2
	v_mov_b32_e32 v117, v2
	v_mov_b32_e32 v126, v2
	v_mov_b32_e32 v127, v2
	v_mov_b32_e32 v128, v2
	v_mov_b32_e32 v129, v2
	v_mov_b32_e32 v70, v2
	v_mov_b32_e32 v71, v2
	v_mov_b32_e32 v72, v2
	v_mov_b32_e32 v73, v2
	v_mov_b32_e32 v78, v2
	v_mov_b32_e32 v79, v2
	v_mov_b32_e32 v80, v2
	v_mov_b32_e32 v81, v2
	v_mov_b32_e32 v86, v2
	v_mov_b32_e32 v87, v2
	v_mov_b32_e32 v88, v2
	v_mov_b32_e32 v89, v2
	v_mov_b32_e32 v94, v2
	v_mov_b32_e32 v95, v2
	v_mov_b32_e32 v96, v2
	v_mov_b32_e32 v97, v2
	v_mov_b32_e32 v102, v2
	v_mov_b32_e32 v103, v2
	v_mov_b32_e32 v104, v2
	v_mov_b32_e32 v105, v2
	v_mov_b32_e32 v110, v2
	v_mov_b32_e32 v111, v2
	v_mov_b32_e32 v112, v2
	v_mov_b32_e32 v113, v2
	v_mov_b32_e32 v118, v2
	v_mov_b32_e32 v119, v2
	v_mov_b32_e32 v120, v2
	v_mov_b32_e32 v121, v2
	v_mov_b32_e32 v122, v2
	v_mov_b32_e32 v123, v2
	v_mov_b32_e32 v124, v2
	v_mov_b32_e32 v125, v2
	.p2align	6

; #define PG8_STAGE(bufoff, gbase, voff) do { _Pragma("unroll") for (int _i = 0; _i < 2; ++_i) \
;     __builtin_amdgcn_global_load_lds((const unsigned*)((const char*)(gbase) + (voff)[_i]), (LAS unsigned*)(lds + (bufoff) + ldsw + _i * 8192), 16, 0, 0); } while (0)
; #define PG8_WAIT_V(n) asm volatile("s_waitcnt vmcnt(" #n ")" ::: "memory")
; #define PG8_BAR __builtin_amdgcn_s_barrier()
; template <class Epi, class Sched>
; DI void gemm_phase(LAS unsigned char* lds, const Gemm g, const Sched& S, const Epi& E) {
;     ...
;   f32x4 acc[2][2][4][2];
; #pragma unroll
;   for (int a = 0; a < 2; ++a)
; #pragma unroll
;     for (int b = 0; b < 2; ++b)
; #pragma unroll
;       for (int m = 0; m < 4; ++m)
; #pragma unroll
;         for (int n = 0; n < 2; ++n) acc[a][b][m][n] = (f32x4){0.f, 0.f, 0.f, 0.f};
;     ...
;   PG8_STAGE(PG8_SB(0, 0), cB, voffB); PG8_STAGE(PG8_SA(0, 0), cA, voffA); PG8_STAGE(PG8_SB(0, 1), cB + hstepB, voffB); PG8_STAGE(PG8_SA(0, 1), cA + hstep, voffA);
;   if (wr == 1) PG8_BAR;
;   PG8_WAIT_V(4); PG8_BAR;
;   PG8_STAGE(PG8_SB(1, 0), cB + kstep, voffB); PG8_STAGE(PG8_SA(1, 0), cA + kstep, voffA); PG8_STAGE(PG8_SB(1, 1), cB + hstepB + kstep, voffB);
;   PG8_WAIT_V(6); PG8_BAR;
.LBB0_189:
	v_lshl_add_u64 v[4:5], s[2:3], 0, v[0:1]
	v_mov_b32_e32 v131, v1
	v_and_b32_e32 v142, 15, v2
	v_lshrrev_b32_e32 v2, 1, v2
	v_lshl_add_u64 v[6:7], s[2:3], 0, v[130:131]
	v_mov_b32_e32 v135, v1
	v_and_b32_e32 v140, 24, v2
	s_add_i32 m0, s23, 0x18000
	v_lshl_add_u64 v[2:3], v[4:5], 0, s[70:71]
	v_lshl_add_u64 v[8:9], s[12:13], 0, v[134:135]
	v_mov_b32_e32 v133, v1
	s_waitcnt vmcnt(4)
	s_barrier
	global_load_lds_dwordx4 v[2:3], off
	v_lshl_add_u64 v[2:3], v[6:7], 0, s[70:71]
	s_add_i32 m0, s23, 0x1a000
	s_add_i32 s27, s23, 0x8000
	v_lshl_add_u64 v[10:11], s[12:13], 0, v[132:133]
	global_load_lds_dwordx4 v[2:3], off
	v_lshl_add_u64 v[2:3], v[8:9], 0, s[70:71]
	s_mov_b32 m0, s27
	s_add_i32 s29, s23, 0xa000
	v_lshl_add_u64 v[12:13], s[16:17], 0, v[0:1]
	global_load_lds_dwordx4 v[2:3], off
	v_lshl_add_u64 v[2:3], v[10:11], 0, s[70:71]
	s_mov_b32 m0, s29
	v_lshl_add_u64 v[14:15], s[16:17], 0, v[130:131]
	global_load_lds_dwordx4 v[2:3], off
	s_add_i32 m0, s23, 0x1c000
	v_lshl_add_u64 v[2:3], v[12:13], 0, s[70:71]
	global_load_lds_dwordx4 v[2:3], off
	v_lshl_add_u64 v[2:3], v[14:15], 0, s[70:71]
	s_add_i32 m0, s23, 0x1e000
	s_lshl_b32 s16, s19, 5
	global_load_lds_dwordx4 v[2:3], off
	s_waitcnt vmcnt(6)
	s_and_b32 s21, s16, 0x60
	v_mov_b32_e32 v129, 0
	v_lshl_or_b32 v141, s18, 6, v142
	s_cmp_lt_i32 s14, 64
	v_mov_b32_e32 v128, v129
	v_mov_b32_e32 v127, v129
	v_mov_b32_e32 v126, v129
	v_mov_b32_e32 v121, v129
	v_mov_b32_e32 v120, v129
	v_mov_b32_e32 v119, v129
	v_mov_b32_e32 v118, v129
	v_mov_b32_e32 v113, v129
	v_mov_b32_e32 v112, v129
	v_mov_b32_e32 v111, v129
	v_mov_b32_e32 v110, v129
	v_mov_b32_e32 v105, v129
	v_mov_b32_e32 v104, v129
	v_mov_b32_e32 v103, v129
	v_mov_b32_e32 v102, v129
	v_mov_b32_e32 v97, v129
	v_mov_b32_e32 v96, v129
	v_mov_b32_e32 v95, v129
	v_mov_b32_e32 v94, v129
	v_mov_b32_e32 v89, v129
	v_mov_b32_e32 v88, v129
	v_mov_b32_e32 v87, v129
	v_mov_b32_e32 v86, v129
	v_mov_b32_e32 v81, v129
	v_mov_b32_e32 v80, v129
	v_mov_b32_e32 v79, v129
	v_mov_b32_e32 v78, v129
	v_mov_b32_e32 v73, v129
	v_mov_b32_e32 v72, v129
	v_mov_b32_e32 v71, v129
	v_mov_b32_e32 v70, v129
	v_mov_b32_e32 v125, v129
	v_mov_b32_e32 v124, v129
	v_mov_b32_e32 v123, v129
	v_mov_b32_e32 v122, v129
	v_mov_b32_e32 v117, v129
	v_mov_b32_e32 v116, v129
	v_mov_b32_e32 v115, v129
	v_mov_b32_e32 v114, v129
	v_mov_b32_e32 v109, v129
	v_mov_b32_e32 v108, v129
	v_mov_b32_e32 v107, v129
	v_mov_b32_e32 v106, v129
	v_mov_b32_e32 v101, v129
	v_mov_b32_e32 v100, v129
	v_mov_b32_e32 v99, v129
	v_mov_b32_e32 v98, v129
	v_mov_b32_e32 v93, v129
	v_mov_b32_e32 v92, v129
	v_mov_b32_e32 v91, v129
	v_mov_b32_e32 v90, v129
	v_mov_b32_e32 v85, v129
	v_mov_b32_e32 v84, v129
	v_mov_b32_e32 v83, v129
	v_mov_b32_e32 v82, v129
	v_mov_b32_e32 v77, v129
	v_mov_b32_e32 v76, v129
	v_mov_b32_e32 v75, v129
	v_mov_b32_e32 v74, v129
	v_mov_b32_e32 v69, v129
	v_mov_b32_e32 v68, v129
	v_mov_b32_e32 v67, v129
	v_mov_b32_e32 v66, v129
	v_mov_b32_e32 v65, v129
	v_mov_b32_e32 v64, v129
	v_mov_b32_e32 v63, v129
	v_mov_b32_e32 v62, v129
	v_mov_b32_e32 v57, v129
	v_mov_b32_e32 v56, v129
	v_mov_b32_e32 v55, v129
	v_mov_b32_e32 v54, v129
	v_mov_b32_e32 v49, v129
	v_mov_b32_e32 v48, v129
	v_mov_b32_e32 v47, v129
	v_mov_b32_e32 v46, v129
	v_mov_b32_e32 v41, v129
	v_mov_b32_e32 v40, v129
	v_mov_b32_e32 v39, v129
	v_mov_b32_e32 v38, v129
	v_mov_b32_e32 v33, v129
	v_mov_b32_e32 v32, v129
	v_mov_b32_e32 v31, v129
	v_mov_b32_e32 v30, v129
	v_mov_b32_e32 v25, v129
	v_mov_b32_e32 v24, v129
	v_mov_b32_e32 v23, v129
	v_mov_b32_e32 v22, v129
	v_mov_b32_e32 v17, v129
	v_mov_b32_e32 v16, v129
	v_mov_b32_e32 v15, v129
	v_mov_b32_e32 v14, v129
	v_mov_b32_e32 v9, v129
	v_mov_b32_e32 v8, v129
	v_mov_b32_e32 v7, v129
	v_mov_b32_e32 v6, v129
	v_mov_b32_e32 v61, v129
	v_mov_b32_e32 v60, v129
	v_mov_b32_e32 v59, v129
	v_mov_b32_e32 v58, v129
	v_mov_b32_e32 v53, v129
	v_mov_b32_e32 v52, v129
	v_mov_b32_e32 v51, v129
	v_mov_b32_e32 v50, v129
	v_mov_b32_e32 v45, v129
	v_mov_b32_e32 v44, v129
	v_mov_b32_e32 v43, v129
	v_mov_b32_e32 v42, v129
	v_mov_b32_e32 v37, v129
	v_mov_b32_e32 v36, v129
	v_mov_b32_e32 v35, v129
	v_mov_b32_e32 v34, v129
	v_mov_b32_e32 v29, v129
	v_mov_b32_e32 v28, v129
	v_mov_b32_e32 v27, v129
	v_mov_b32_e32 v26, v129
	v_mov_b32_e32 v21, v129
	v_mov_b32_e32 v20, v129
	v_mov_b32_e32 v19, v129
	v_mov_b32_e32 v18, v129
	v_mov_b32_e32 v13, v129
	v_mov_b32_e32 v12, v129
	v_mov_b32_e32 v11, v129
	v_mov_b32_e32 v10, v129
	v_mov_b32_e32 v5, v129
	v_mov_b32_e32 v4, v129
	v_mov_b32_e32 v3, v129
	v_mov_b32_e32 v2, v129
	s_barrier
;   DI bool next(int i, Unit& o) const { if (i != 0 || !valid) return false; o = u; return true; }
; template <class Epi, class Sched>
; DI void gemm_phase(LAS unsigned char* lds, const Gemm g, const Sched& S, const Epi& E) {
;     ...
;     int R, C; stage_rc(tid * 16 + i * 8192, R, C);
;     int Rb = R;
;     if (Epi::BMAP == 1) Rb = (R & ~31) + perm32(R & 31);
;     if (Epi::BMAP == 2) Rb = 64 * (R >> 5) + perm32(R & 31);
;     voffA[i] = (unsigned)(R * K + C) * 2u; voffB[i] = (unsigned)(Rb * K + C) * 2u;
;   }
;   const size_t kstep = (size_t)(BK * 2);
;   const size_t hstep = (size_t)HALF * K * 2;
;   const size_t hstepB = (Epi::BMAP == 2) ? (size_t)32 * K * 2 : hstep;
;   const size_t tstep = 2 * hstep;
;   const unsigned ldsw = (unsigned)wid * 1024u;
;   const int aoff = lds_byte(wr * 64 + fr, fq * 8), boff = lds_byte(wc * 32 + fr, fq * 8);
;     ...
;   Unit cur, nxt; int ui = 0;
;   if (!S.next(0, cur)) return;
;   f32x4 acc[2][2][4][2];
; #pragma unroll
;   for (int a = 0; a < 2; ++a)
; #pragma unroll
;     for (int b = 0; b < 2; ++b)
; #pragma unroll
;       for (int m = 0; m < 4; ++m)
; #pragma unroll
;         for (int n = 0; n < 2; ++n) acc[a][b][m][n] = (f32x4){0.f, 0.f, 0.f, 0.f};
	s_cbranch_scc1 .LBB0_192
	s_lshr_b32 s15, s15, 26
	s_add_i32 s15, s14, s15
	s_ashr_i32 s30, s15, 6
	v_lshlrev_b32_e32 v2, 6, v141
	v_lshlrev_b32_e32 v3, 1, v140
	s_movk_i32 s15, 0x3c0
	v_lshlrev_b32_e32 v4, 2, v141
	v_and_or_b32 v2, v2, s15, v3
	s_lshl_b32 s15, s18, 13
	v_and_b32_e32 v4, 32, v4
	v_bitop3_b32 v4, v2, s15, v4 bitop3:0xde
	v_lshl_or_b32 v2, v142, 6, v3
	v_lshlrev_b32_e32 v3, 2, v142
	s_lshl_b32 s15, s21, 7
	v_and_b32_e32 v3, 32, v3
	v_readlane_b32 s16, v253, 35
	s_add_i32 s31, s30, -2
	v_bitop3_b32 v142, v2, s15, v3 bitop3:0xde
	s_mul_hi_i32 s15, s16, s14
	s_mul_i32 s14, s16, s14
	v_add_u32_e32 v2, v144, v136
	s_add_u32 s14, s86, s14
	v_add_lshl_u32 v2, v2, v137, 1
	v_mov_b32_e32 v3, v1
	s_addc_u32 s15, s87, s15
	v_lshl_add_u64 v[136:137], s[14:15], 0, v[2:3]
	v_add_u32_e32 v2, v143, v138
	v_add_lshl_u32 v2, v2, v139, 1
	v_lshl_add_u64 v[138:139], s[14:15], 0, v[2:3]
	v_mov_b32_e32 v2, 0
	s_mov_b32 s16, 0
	s_mov_b64 s[14:15], 0x2000080
	v_add_u32_e32 v143, 16, v4
	v_mov_b32_e32 v3, v2
	v_mov_b32_e32 v4, v2
	v_mov_b32_e32 v5, v2
	v_mov_b32_e32 v10, v2
	v_mov_b32_e32 v11, v2
	v_mov_b32_e32 v12, v2
	v_mov_b32_e32 v13, v2
	v_mov_b32_e32 v18, v2
	v_mov_b32_e32 v19, v2
	v_mov_b32_e32 v20, v2
	v_mov_b32_e32 v21, v2
	v_mov_b32_e32 v26, v2
	v_mov_b32_e32 v27, v2
	v_mov_b32_e32 v28, v2
	v_mov_b32_e32 v29, v2
	v_mov_b32_e32 v34, v2
	v_mov_b32_e32 v35, v2
	v_mov_b32_e32 v36, v2
	v_mov_b32_e32 v37, v2
	v_mov_b32_e32 v42, v2
	v_mov_b32_e32 v43, v2
	v_mov_b32_e32 v44, v2
	v_mov_b32_e32 v45, v2
	v_mov_b32_e32 v50, v2
	v_mov_b32_e32 v51, v2
	v_mov_b32_e32 v52, v2
	v_mov_b32_e32 v53, v2
	v_mov_b32_e32 v58, v2
	v_mov_b32_e32 v59, v2
	v_mov_b32_e32 v60, v2
	v_mov_b32_e32 v61, v2
	v_mov_b32_e32 v6, v2
	v_mov_b32_e32 v7, v2
	v_mov_b32_e32 v8, v2
	v_mov_b32_e32 v9, v2
	v_mov_b32_e32 v14, v2
	v_mov_b32_e32 v15, v2
	v_mov_b32_e32 v16, v2
	v_mov_b32_e32 v17, v2
	v_mov_b32_e32 v22, v2
	v_mov_b32_e32 v23, v2
	v_mov_b32_e32 v24, v2
	v_mov_b32_e32 v25, v2
	v_mov_b32_e32 v30, v2
	v_mov_b32_e32 v31, v2
	v_mov_b32_e32 v32, v2
	v_mov_b32_e32 v33, v2
	v_mov_b32_e32 v38, v2
	v_mov_b32_e32 v39, v2
	v_mov_b32_e32 v40, v2
	v_mov_b32_e32 v41, v2
	v_mov_b32_e32 v46, v2
	v_mov_b32_e32 v47, v2
	v_mov_b32_e32 v48, v2
	v_mov_b32_e32 v49, v2
	v_mov_b32_e32 v54, v2
	v_mov_b32_e32 v55, v2
	v_mov_b32_e32 v56, v2
	v_mov_b32_e32 v57, v2
	v_mov_b32_e32 v62, v2
	v_mov_b32_e32 v63, v2
	v_mov_b32_e32 v64, v2
	v_mov_b32_e32 v65, v2
	v_mov_b32_e32 v66, v2
	v_mov_b32_e32 v67, v2
	v_mov_b32_e32 v68, v2
	v_mov_b32_e32 v69, v2
	v_mov_b32_e32 v74, v2
	v_mov_b32_e32 v75, v2
	v_mov_b32_e32 v76, v2
	v_mov_b32_e32 v77, v2
	v_mov_b32_e32 v82, v2
	v_mov_b32_e32 v83, v2
	v_mov_b32_e32 v84, v2
	v_mov_b32_e32 v85, v2
	v_mov_b32_e32 v90, v2
	v_mov_b32_e32 v91, v2
	v_mov_b32_e32 v92, v2
	v_mov_b32_e32 v93, v2
	v_mov_b32_e32 v98, v2
	v_mov_b32_e32 v99, v2
	v_mov_b32_e32 v100, v2
	v_mov_b32_e32 v101, v2
	v_mov_b32_e32 v106, v2
	v_mov_b32_e32 v107, v2
	v_mov_b32_e32 v108, v2
	v_mov_b32_e32 v109, v2
	v_mov_b32_e32 v114, v2
	v_mov_b32_e32 v115, v2
	v_mov_b32_e32 v116, v2
	v_mov_b32_e32 v117, v2
	v_mov_b32_e32 v122, v2
	v_mov_b32_e32 v123, v2
	v_mov_b32_e32 v124, v2
	v_mov_b32_e32 v125, v2
	v_mov_b32_e32 v70, v2
	v_mov_b32_e32 v71, v2
	v_mov_b32_e32 v72, v2
	v_mov_b32_e32 v73, v2
	v_mov_b32_e32 v78, v2
	v_mov_b32_e32 v79, v2
	v_mov_b32_e32 v80, v2
	v_mov_b32_e32 v81, v2
	v_mov_b32_e32 v86, v2
	v_mov_b32_e32 v87, v2
	v_mov_b32_e32 v88, v2
	v_mov_b32_e32 v89, v2
	v_mov_b32_e32 v94, v2
	v_mov_b32_e32 v95, v2
	v_mov_b32_e32 v96, v2
	v_mov_b32_e32 v97, v2
	v_mov_b32_e32 v102, v2
	v_mov_b32_e32 v103, v2
	v_mov_b32_e32 v104, v2
	v_mov_b32_e32 v105, v2
	v_mov_b32_e32 v110, v2
	v_mov_b32_e32 v111, v2
	v_mov_b32_e32 v112, v2
	v_mov_b32_e32 v113, v2
	v_mov_b32_e32 v118, v2
	v_mov_b32_e32 v119, v2
	v_mov_b32_e32 v120, v2
	v_mov_b32_e32 v121, v2
	v_mov_b32_e32 v126, v2
	v_mov_b32_e32 v127, v2
	v_mov_b32_e32 v128, v2
	v_mov_b32_e32 v129, v2
	.p2align	6

; #define PG8_STAGE(bufoff, gbase, voff) do { _Pragma("unroll") for (int _i = 0; _i < 2; ++_i) \
;     __builtin_amdgcn_global_load_lds((const unsigned*)((const char*)(gbase) + (voff)[_i]), (LAS unsigned*)(lds + (bufoff) + ldsw + _i * 8192), 16, 0, 0); } while (0)
; #define PG8_WAIT_V(n) asm volatile("s_waitcnt vmcnt(" #n ")" ::: "memory")
; #define PG8_BAR __builtin_amdgcn_s_barrier()
; template <class Epi, class Sched>
; DI void gemm_phase(LAS unsigned char* lds, const Gemm g, const Sched& S, const Epi& E) {
;     ...
;   f32x4 acc[2][2][4][2];
; #pragma unroll
;   for (int a = 0; a < 2; ++a)
; #pragma unroll
;     for (int b = 0; b < 2; ++b)
; #pragma unroll
;       for (int m = 0; m < 4; ++m)
; #pragma unroll
;         for (int n = 0; n < 2; ++n) acc[a][b][m][n] = (f32x4){0.f, 0.f, 0.f, 0.f};
;     ...
;   PG8_STAGE(PG8_SB(0, 0), cB, voffB); PG8_STAGE(PG8_SA(0, 0), cA, voffA); PG8_STAGE(PG8_SB(0, 1), cB + hstepB, voffB); PG8_STAGE(PG8_SA(0, 1), cA + hstep, voffA);
;   if (wr == 1) PG8_BAR;
;   PG8_WAIT_V(4); PG8_BAR;
;   PG8_STAGE(PG8_SB(1, 0), cB + kstep, voffB); PG8_STAGE(PG8_SA(1, 0), cA + kstep, voffA); PG8_STAGE(PG8_SB(1, 1), cB + hstepB + kstep, voffB);
;   PG8_WAIT_V(6); PG8_BAR;
.LBB0_215:
	v_lshl_add_u64 v[4:5], s[12:13], 0, v[0:1]
	v_mov_b32_e32 v131, v1
	v_lshl_add_u64 v[6:7], s[12:13], 0, v[130:131]
	v_and_b32_e32 v132, 15, v2
	v_bfe_u32 v136, v2, 4, 2
	s_add_i32 m0, s30, 0x18000
	v_lshl_add_u64 v[2:3], v[4:5], 0, s[70:71]
	v_lshl_add_u64 v[8:9], s[14:15], 0, v[0:1]
	s_waitcnt vmcnt(4)
	s_barrier
	global_load_lds_dwordx4 v[2:3], off
	v_lshl_add_u64 v[2:3], v[6:7], 0, s[70:71]
	s_add_i32 m0, s30, 0x1a000
	s_add_i32 s36, s30, 0x8000
	v_lshl_add_u64 v[10:11], s[14:15], 0, v[130:131]
	global_load_lds_dwordx4 v[2:3], off
	v_lshl_add_u64 v[2:3], v[8:9], 0, s[70:71]
	s_mov_b32 m0, s36
	s_add_i32 s37, s30, 0xa000
	v_lshl_add_u64 v[12:13], s[18:19], 0, v[0:1]
	global_load_lds_dwordx4 v[2:3], off
	v_lshl_add_u64 v[2:3], v[10:11], 0, s[70:71]
	s_mov_b32 m0, s37
	v_lshl_add_u64 v[14:15], s[18:19], 0, v[130:131]
	global_load_lds_dwordx4 v[2:3], off
	s_add_i32 m0, s30, 0x1c000
	v_lshl_add_u64 v[2:3], v[12:13], 0, s[70:71]
	global_load_lds_dwordx4 v[2:3], off
	v_lshl_add_u64 v[2:3], v[14:15], 0, s[70:71]
	s_add_i32 m0, s30, 0x1e000
	s_lshl_b32 s18, s21, 5
	global_load_lds_dwordx4 v[2:3], off
	s_waitcnt vmcnt(6)
	s_and_b32 s27, s18, 0x60
	v_mov_b32_e32 v129, 0
	v_lshl_or_b32 v146, s20, 6, v132
	s_cmp_lt_i32 s16, 64
	v_mov_b32_e32 v128, v129
	v_mov_b32_e32 v127, v129
	v_mov_b32_e32 v126, v129
	v_mov_b32_e32 v125, v129
	v_mov_b32_e32 v124, v129
	v_mov_b32_e32 v123, v129
	v_mov_b32_e32 v122, v129
	v_mov_b32_e32 v113, v129
	v_mov_b32_e32 v112, v129
	v_mov_b32_e32 v111, v129
	v_mov_b32_e32 v110, v129
	v_mov_b32_e32 v109, v129
	v_mov_b32_e32 v108, v129
	v_mov_b32_e32 v107, v129
	v_mov_b32_e32 v106, v129
	v_mov_b32_e32 v97, v129
	v_mov_b32_e32 v96, v129
	v_mov_b32_e32 v95, v129
	v_mov_b32_e32 v94, v129
	v_mov_b32_e32 v93, v129
	v_mov_b32_e32 v92, v129
	v_mov_b32_e32 v91, v129
	v_mov_b32_e32 v90, v129
	v_mov_b32_e32 v81, v129
	v_mov_b32_e32 v80, v129
	v_mov_b32_e32 v79, v129
	v_mov_b32_e32 v78, v129
	v_mov_b32_e32 v77, v129
	v_mov_b32_e32 v76, v129
	v_mov_b32_e32 v75, v129
	v_mov_b32_e32 v74, v129
	v_mov_b32_e32 v121, v129
	v_mov_b32_e32 v120, v129
	v_mov_b32_e32 v119, v129
	v_mov_b32_e32 v118, v129
	v_mov_b32_e32 v117, v129
	v_mov_b32_e32 v116, v129
	v_mov_b32_e32 v115, v129
	v_mov_b32_e32 v114, v129
	v_mov_b32_e32 v105, v129
	v_mov_b32_e32 v104, v129
	v_mov_b32_e32 v103, v129
	v_mov_b32_e32 v102, v129
	v_mov_b32_e32 v101, v129
	v_mov_b32_e32 v100, v129
	v_mov_b32_e32 v99, v129
	v_mov_b32_e32 v98, v129
	v_mov_b32_e32 v89, v129
	v_mov_b32_e32 v88, v129
	v_mov_b32_e32 v87, v129
	v_mov_b32_e32 v86, v129
	v_mov_b32_e32 v85, v129
	v_mov_b32_e32 v84, v129
	v_mov_b32_e32 v83, v129
	v_mov_b32_e32 v82, v129
	v_mov_b32_e32 v73, v129
	v_mov_b32_e32 v72, v129
	v_mov_b32_e32 v71, v129
	v_mov_b32_e32 v70, v129
	v_mov_b32_e32 v69, v129
	v_mov_b32_e32 v68, v129
	v_mov_b32_e32 v67, v129
	v_mov_b32_e32 v66, v129
	v_mov_b32_e32 v65, v129
	v_mov_b32_e32 v64, v129
	v_mov_b32_e32 v63, v129
	v_mov_b32_e32 v62, v129
	v_mov_b32_e32 v61, v129
	v_mov_b32_e32 v60, v129
	v_mov_b32_e32 v59, v129
	v_mov_b32_e32 v58, v129
	v_mov_b32_e32 v53, v129
	v_mov_b32_e32 v52, v129
	v_mov_b32_e32 v51, v129
	v_mov_b32_e32 v50, v129
	v_mov_b32_e32 v45, v129
	v_mov_b32_e32 v44, v129
	v_mov_b32_e32 v43, v129
	v_mov_b32_e32 v42, v129
	v_mov_b32_e32 v37, v129
	v_mov_b32_e32 v36, v129
	v_mov_b32_e32 v35, v129
	v_mov_b32_e32 v34, v129
	v_mov_b32_e32 v29, v129
	v_mov_b32_e32 v28, v129
	v_mov_b32_e32 v27, v129
	v_mov_b32_e32 v26, v129
	v_mov_b32_e32 v17, v129
	v_mov_b32_e32 v16, v129
	v_mov_b32_e32 v15, v129
	v_mov_b32_e32 v14, v129
	v_mov_b32_e32 v13, v129
	v_mov_b32_e32 v12, v129
	v_mov_b32_e32 v11, v129
	v_mov_b32_e32 v10, v129
	v_mov_b32_e32 v57, v129
	v_mov_b32_e32 v56, v129
	v_mov_b32_e32 v55, v129
	v_mov_b32_e32 v54, v129
	v_mov_b32_e32 v49, v129
	v_mov_b32_e32 v48, v129
	v_mov_b32_e32 v47, v129
	v_mov_b32_e32 v46, v129
	v_mov_b32_e32 v41, v129
	v_mov_b32_e32 v40, v129
	v_mov_b32_e32 v39, v129
	v_mov_b32_e32 v38, v129
	v_mov_b32_e32 v33, v129
	v_mov_b32_e32 v32, v129
	v_mov_b32_e32 v31, v129
	v_mov_b32_e32 v30, v129
	v_mov_b32_e32 v25, v129
	v_mov_b32_e32 v24, v129
	v_mov_b32_e32 v23, v129
	v_mov_b32_e32 v22, v129
	v_mov_b32_e32 v21, v129
	v_mov_b32_e32 v20, v129
	v_mov_b32_e32 v19, v129
	v_mov_b32_e32 v18, v129
	v_mov_b32_e32 v9, v129
	v_mov_b32_e32 v8, v129
	v_mov_b32_e32 v7, v129
	v_mov_b32_e32 v6, v129
	v_mov_b32_e32 v5, v129
	v_mov_b32_e32 v4, v129
	v_mov_b32_e32 v3, v129
	v_mov_b32_e32 v2, v129
	s_barrier
;   DI bool next(int i, Unit& o) const { if (i != 0 || !valid) return false; o = u; return true; }
; template <class Epi, class Sched>
; DI void gemm_phase(LAS unsigned char* lds, const Gemm g, const Sched& S, const Epi& E) {
;     ...
;     voffA[i] = (unsigned)(R * K + C) * 2u; voffB[i] = (unsigned)(Rb * K + C) * 2u;
;   }
;   const size_t kstep = (size_t)(BK * 2);
;   const size_t hstep = (size_t)HALF * K * 2;
;   const size_t hstepB = (Epi::BMAP == 2) ? (size_t)32 * K * 2 : hstep;
;   const size_t tstep = 2 * hstep;
;   const unsigned ldsw = (unsigned)wid * 1024u;
;   const int aoff = lds_byte(wr * 64 + fr, fq * 8), boff = lds_byte(wc * 32 + fr, fq * 8);
;     ...
;   Unit cur, nxt; int ui = 0;
;   if (!S.next(0, cur)) return;
;   f32x4 acc[2][2][4][2];
; #pragma unroll
;   for (int a = 0; a < 2; ++a)
; #pragma unroll
;     for (int b = 0; b < 2; ++b)
; #pragma unroll
;       for (int m = 0; m < 4; ++m)
; #pragma unroll
;         for (int n = 0; n < 2; ++n) acc[a][b][m][n] = (f32x4){0.f, 0.f, 0.f, 0.f};
	s_cbranch_scc1 .LBB0_218
	s_lshr_b32 s18, s17, 26
	s_add_i32 s18, s16, s18
	s_ashr_i32 s38, s18, 6
	v_lshlrev_b32_e32 v2, 4, v136
	v_lshlrev_b32_e32 v3, 6, v146
	s_movk_i32 s18, 0x3c0
	v_lshlrev_b32_e32 v4, 2, v146
	v_and_or_b32 v3, v3, s18, v2
	s_lshl_b32 s18, s20, 13
	v_and_b32_e32 v4, 32, v4
	v_bitop3_b32 v3, v3, s18, v4 bitop3:0xde
	v_lshlrev_b32_e32 v4, 2, v132
	v_lshl_or_b32 v2, v132, 6, v2
	s_lshl_b32 s18, s27, 7
	v_and_b32_e32 v4, 32, v4
	v_bitop3_b32 v137, v2, s18, v4 bitop3:0xde
	s_lshl_b64 s[18:19], s[2:3], 9
	s_or_b32 s3, s18, 0x100
	s_mul_i32 s17, s3, s17
	s_mul_hi_u32 s18, s3, s16
	s_add_i32 s17, s18, s17
	s_mul_i32 s18, s19, s16
	s_add_i32 s39, s38, -2
	s_add_i32 s17, s17, s18
	s_mul_i32 s3, s3, s16
	s_add_u32 s16, s90, s3
	s_addc_u32 s17, s91, s17
	v_mov_b32_e32 v2, 0
	v_lshl_add_u64 v[132:133], s[16:17], 0, v[0:1]
	v_lshl_add_u64 v[134:135], s[16:17], 0, v[130:131]
	s_mov_b32 s3, 0
	s_mov_b64 s[16:17], 0x80
	v_add_u32_e32 v138, 16, v3
	v_mov_b32_e32 v3, v2
	v_mov_b32_e32 v4, v2
	v_mov_b32_e32 v5, v2
	v_mov_b32_e32 v6, v2
	v_mov_b32_e32 v7, v2
	v_mov_b32_e32 v8, v2
	v_mov_b32_e32 v9, v2
	v_mov_b32_e32 v18, v2
	v_mov_b32_e32 v19, v2
	v_mov_b32_e32 v20, v2
	v_mov_b32_e32 v21, v2
	v_mov_b32_e32 v22, v2
	v_mov_b32_e32 v23, v2
	v_mov_b32_e32 v24, v2
	v_mov_b32_e32 v25, v2
	v_mov_b32_e32 v30, v2
	v_mov_b32_e32 v31, v2
	v_mov_b32_e32 v32, v2
	v_mov_b32_e32 v33, v2
	v_mov_b32_e32 v38, v2
	v_mov_b32_e32 v39, v2
	v_mov_b32_e32 v40, v2
	v_mov_b32_e32 v41, v2
	v_mov_b32_e32 v46, v2
	v_mov_b32_e32 v47, v2
	v_mov_b32_e32 v48, v2
	v_mov_b32_e32 v49, v2
	v_mov_b32_e32 v54, v2
	v_mov_b32_e32 v55, v2
	v_mov_b32_e32 v56, v2
	v_mov_b32_e32 v57, v2
	v_mov_b32_e32 v10, v2
	v_mov_b32_e32 v11, v2
	v_mov_b32_e32 v12, v2
	v_mov_b32_e32 v13, v2
	v_mov_b32_e32 v14, v2
	v_mov_b32_e32 v15, v2
	v_mov_b32_e32 v16, v2
	v_mov_b32_e32 v17, v2
	v_mov_b32_e32 v26, v2
	v_mov_b32_e32 v27, v2
	v_mov_b32_e32 v28, v2
	v_mov_b32_e32 v29, v2
	v_mov_b32_e32 v34, v2
	v_mov_b32_e32 v35, v2
	v_mov_b32_e32 v36, v2
	v_mov_b32_e32 v37, v2
	v_mov_b32_e32 v42, v2
	v_mov_b32_e32 v43, v2
	v_mov_b32_e32 v44, v2
	v_mov_b32_e32 v45, v2
	v_mov_b32_e32 v50, v2
	v_mov_b32_e32 v51, v2
	v_mov_b32_e32 v52, v2
	v_mov_b32_e32 v53, v2
	v_mov_b32_e32 v58, v2
	v_mov_b32_e32 v59, v2
	v_mov_b32_e32 v60, v2
	v_mov_b32_e32 v61, v2
	v_mov_b32_e32 v62, v2
	v_mov_b32_e32 v63, v2
	v_mov_b32_e32 v64, v2
	v_mov_b32_e32 v65, v2
	v_mov_b32_e32 v66, v2
	v_mov_b32_e32 v67, v2
	v_mov_b32_e32 v68, v2
	v_mov_b32_e32 v69, v2
	v_mov_b32_e32 v70, v2
	v_mov_b32_e32 v71, v2
	v_mov_b32_e32 v72, v2
	v_mov_b32_e32 v73, v2
	v_mov_b32_e32 v82, v2
	v_mov_b32_e32 v83, v2
	v_mov_b32_e32 v84, v2
	v_mov_b32_e32 v85, v2
	v_mov_b32_e32 v86, v2
	v_mov_b32_e32 v87, v2
	v_mov_b32_e32 v88, v2
	v_mov_b32_e32 v89, v2
	v_mov_b32_e32 v98, v2
	v_mov_b32_e32 v99, v2
	v_mov_b32_e32 v100, v2
	v_mov_b32_e32 v101, v2
	v_mov_b32_e32 v102, v2
	v_mov_b32_e32 v103, v2
	v_mov_b32_e32 v104, v2
	v_mov_b32_e32 v105, v2
	v_mov_b32_e32 v114, v2
	v_mov_b32_e32 v115, v2
	v_mov_b32_e32 v116, v2
	v_mov_b32_e32 v117, v2
	v_mov_b32_e32 v118, v2
	v_mov_b32_e32 v119, v2
	v_mov_b32_e32 v120, v2
	v_mov_b32_e32 v121, v2
	v_mov_b32_e32 v74, v2
	v_mov_b32_e32 v75, v2
	v_mov_b32_e32 v76, v2
	v_mov_b32_e32 v77, v2
	v_mov_b32_e32 v78, v2
	v_mov_b32_e32 v79, v2
	v_mov_b32_e32 v80, v2
	v_mov_b32_e32 v81, v2
	v_mov_b32_e32 v90, v2
	v_mov_b32_e32 v91, v2
	v_mov_b32_e32 v92, v2
	v_mov_b32_e32 v93, v2
	v_mov_b32_e32 v94, v2
	v_mov_b32_e32 v95, v2
	v_mov_b32_e32 v96, v2
	v_mov_b32_e32 v97, v2
	v_mov_b32_e32 v106, v2
	v_mov_b32_e32 v107, v2
	v_mov_b32_e32 v108, v2
	v_mov_b32_e32 v109, v2
	v_mov_b32_e32 v110, v2
	v_mov_b32_e32 v111, v2
	v_mov_b32_e32 v112, v2
	v_mov_b32_e32 v113, v2
	v_mov_b32_e32 v122, v2
	v_mov_b32_e32 v123, v2
	v_mov_b32_e32 v124, v2
	v_mov_b32_e32 v125, v2
	v_mov_b32_e32 v126, v2
	v_mov_b32_e32 v127, v2
	v_mov_b32_e32 v128, v2
	v_mov_b32_e32 v129, v2
	.p2align	6

; DI void attn_item(const Params& p, int layer, int item, char* smem) {
;     ...
;   if (item < NAT_C) { mode = 0; b = item / 96; int rem = item % 96; hh = rem >> 4; qb = rem & 15; }
;   else if (item < NAT_C + NAT_B) { int it = item - NAT_C; mode = 1; b = it >> 6; hh = (it & 63) >> 4; qb = it & 15; }
;   else if (item < NAT_LAT) { int it = item - NAT_C - NAT_B; mode = 2; b = it / 96; int rem = it % 96; hh = rem >> 4; qb = rem & 15; }
;   else { int it = item - NAT_LAT; mode = 3; b = it >> 4; hh = it & 15; qb = 0; }
;   int qchunk, kchunk, vchunk, head16, t0 = 0, t1 = 0, qpos0 = qb * 256;
;   bool hasSink = false; float sinkv = 0.f;
;   int maskmode = 0;
;   if (mode == 0) { qchunk = 22 + hh; kchunk = 28 + hh / 3; vchunk = 30 + hh / 3; head16 = 10 + hh; t0 = 0; t1 = 64; }
;   else if (mode == 1) {
;     qchunk = 10 + hh; kchunk = 14 + hh; vchunk = 18 + hh; head16 = 6 + hh; maskmode = 1;
;     t0 = min(max(4 * qb - 4, 0), 56); t1 = min(max(4 * qb + 3 - 4, 0), 56) + 8;
;   } else if (mode == 2) {
;     qchunk = hh; kchunk = 6 + hh / 3; vchunk = 8 + hh / 3; head16 = hh; maskmode = 2;
;     t0 = max(0, 4 * qb - 2); t1 = min(64, 4 * qb + 6); hasSink = true; sinkv = p.sink[layer * 6 + hh];
;   } else {
;     head16 = hh; qpos0 = 4096;
;     if (hh < 6) { qchunk = hh; kchunk = 6 + hh / 3; vchunk = 8 + hh / 3; hasSink = true; sinkv = p.sink[layer * 6 + hh]; }
;     else if (hh < 10) { int hb = hh - 6; qchunk = 10 + hb; kchunk = 14 + hb; vchunk = 18 + hb; }
;     else { int hc = hh - 10; qchunk = 22 + hc; kchunk = 28 + hc / 3; vchunk = 30 + hc / 3; }
;   }
;   const int n_it = 4 + (t1 - t0);
;   const u16* Qb = p.QKV + (size_t)(b * 32 + qchunk) * LTOT * 64;
;   const u16* Kb = p.QKV + (size_t)(b * 32 + kchunk) * LTOT * 64;
;   const u16* Vb = p.QKV + (size_t)(b * 32 + vchunk) * LTOT * 64;
;   float* s_rpb = (float*)(smem + RPB_OFF);
;   if (mode == 1) {
;     const float* rp = p.rpb + (size_t)(layer * 4 + hh) * 465;
;     for (int e = tid; e < 465; e += NTHR) s_rpb[e] = rp[e] * LOG2E;
;   }
;   const int qpos = qpos0 + wid * 32 + l32;
;   bf16x8 qf[4];
; #pragma unroll
;   for (int s = 0; s < 4; ++s) qf[s] = *(const bf16x8*)(Qb + (size_t)qpos * 64 + s * 16 + h * 8);
;   f32x16 o0, o1;
; #pragma unroll
;   for (int r = 0; r < 16; ++r) { o0[r] = 0.f; o1[r] = 0.f; }
;   const int btype = (mode == 3) ? (hh < 6 ? 0 : (hh < 10 ? 1 : 2)) : (mode == 0 ? 2 : (mode == 1 ? 1 : 0));
.LBB0_259:
	s_mul_hi_i32 s0, s14, 0x2aaaaaab
	s_lshr_b32 s1, s0, 31
	s_ashr_i32 s5, s0, 4
	s_add_i32 s5, s5, s1
	s_mul_i32 s0, s5, 0x60
	s_sub_i32 s0, s14, s0
	v_mov_b32_e32 v32, v213
	s_ashr_i32 s4, s0, 4
	s_lshl_b32 s0, s0, 8
	s_and_b32 s8, s0, 0xf00
	s_lshl_b32 s0, s5, 5
	v_ashrrev_i32_e32 v0, 1, v32
	s_add_i32 s1, s4, s0
	s_mul_i32 s2, s4, 0x56
	v_and_b32_e32 v0, 0xffffffe0, v0
	v_and_b32_e32 v36, 31, v32
	s_bfe_u32 s3, s2, 0x1000f
	s_bfe_u32 s2, s2, 0x80008
	s_add_i32 s1, s1, 22
	v_add_u32_e32 v0, s8, v0
	s_add_i32 s2, s2, s3
	s_mul_hi_i32 s3, s1, 0x88000
	s_mul_i32 s1, s1, 0x88000
	v_or_b32_e32 v134, v0, v36
	s_add_u32 s6, s88, s1
	v_ashrrev_i32_e32 v135, 31, v134
	v_bfe_u32 v140, v32, 5, 1
	s_addc_u32 s7, s89, s3
	v_lshlrev_b64 v[2:3], 7, v[134:135]
	v_lshl_add_u64 v[2:3], s[6:7], 0, v[2:3]
	v_lshlrev_b32_e32 v18, 4, v140
	v_mov_b32_e32 v19, v1
	v_readlane_b32 s6, v254, 50
	v_lshl_add_u64 v[2:3], v[2:3], 0, v[18:19]
	v_readlane_b32 s7, v254, 51
	global_load_dwordx4 v[98:101], v[2:3], off
	global_load_dwordx4 v[102:105], v[2:3], off offset:32
	global_load_dwordx4 v[106:109], v[2:3], off offset:64
	global_load_dwordx4 v[110:113], v[2:3], off offset:96
	s_sext_i32_i8 s2, s2
	global_load_dword v2, v1, s[6:7] offset:8
	s_add_i32 s2, s0, s2
	s_mul_i32 s3, s2, 0x88000
	s_add_i32 s0, s2, 28
	s_mul_hi_i32 s1, s0, 0x88000
	s_add_i32 s0, s3, 0xee0000
	v_ashrrev_i32_e32 v30, 3, v32
	s_add_u32 s0, s88, s0
	v_ashrrev_i32_e32 v31, 31, v30
	s_addc_u32 s1, s89, s1
	v_lshlrev_b32_e32 v19, 4, v32
	v_lshlrev_b64 v[20:21], 7, v[30:31]
	v_lshl_add_u64 v[136:137], s[0:1], 0, v[20:21]
	s_mov_b32 s6, 0x80000
	s_add_i32 s2, s2, 30
	s_add_i32 s3, s3, 0xff0000
	s_mul_hi_i32 s9, s2, 0x88000
	s_add_u32 s2, s88, s3
	s_addc_u32 s3, s89, s9
	v_mov_b64_e32 v[26:27], s[2:3]
	v_mad_i64_i32 v[138:139], s[2:3], v30, s28, v[26:27]
	s_movk_i32 s3, 0x90
	s_mov_b32 s2, 0x82000
	v_mul_lo_u32 v30, v30, s3
	v_add_u32_e32 v30, 16, v30
	v_add_u32_e32 v144, 16, v18
	v_mul_u32_u24_e32 v145, 0x90, v36
	v_mad_u32_u24 v146, v36, s3, v144
	v_and_b32_e32 v0, 0x70, v19
	v_lshl_add_u64 v[34:35], v[136:137], 0, v[0:1]
	v_add_co_u32_e32 v22, vcc, s6, v34
	v_add_u32_e32 v135, v30, v0
	s_nop 0
	v_addc_co_u32_e32 v23, vcc, 0, v35, vcc
	global_load_dwordx4 v[22:25], v[22:23], off
	v_add_co_u32_e32 v26, vcc, s2, v34
	v_lshl_add_u64 v[74:75], v[138:139], 0, v[0:1]
	s_nop 0
	v_addc_co_u32_e32 v27, vcc, 0, v35, vcc
	global_load_dwordx4 v[26:29], v[26:27], off
	s_movk_i32 s2, 0x2000
	v_lshlrev_b32_e32 v78, 3, v32
	v_and_b32_e32 v78, 8, v78
	v_and_or_b32 v19, v19, s74, v78
	v_add_co_u32_e32 v78, vcc, s2, v74
	v_add_u32_e32 v19, v30, v19
	s_nop 0
	v_addc_co_u32_e32 v79, vcc, 0, v75, vcc
	global_load_dwordx4 v[30:33], v[78:79], off
	s_mov_b32 s2, 0x84000
	v_add_co_u32_e32 v80, vcc, s2, v34
	v_add_u32_e32 v141, 0x2000, v19
	s_nop 0
	v_addc_co_u32_e32 v81, vcc, 0, v35, vcc
	global_load_dwordx4 v[66:69], v[80:81], off
	global_load_dwordx4 v[70:73], v[78:79], off offset:256
	v_lshl_add_u64 v[80:81], s[0:1], 0, v[0:1]
	v_lshl_add_u64 v[76:77], v[80:81], 0, v[20:21]
	s_mov_b32 s0, 0x86000
	v_add_u32_e32 v143, 0x6800, v19
	s_waitcnt vmcnt(5)
	v_xor_b32_e32 v2, 0x80000000, v2
	v_mov_b32_e32 v3, v2
	v_mov_b32_e32 v4, v2
	v_mov_b32_e32 v5, v2
	v_mov_b32_e32 v6, v2
	v_mov_b32_e32 v7, v2
	v_mov_b32_e32 v8, v2
	v_mov_b32_e32 v9, v2
	v_mov_b32_e32 v10, v2
	v_mov_b32_e32 v11, v2
	v_mov_b32_e32 v12, v2
	v_mov_b32_e32 v13, v2
	v_mov_b32_e32 v14, v2
	v_mov_b32_e32 v15, v2
	v_mov_b32_e32 v16, v2
	v_mov_b32_e32 v17, v2
	s_waitcnt vmcnt(4)
	ds_write_b128 v135, v[22:25]
	s_waitcnt vmcnt(2)
	ds_write2_b64 v141, v[30:31], v[32:33] offset0:128 offset1:130
	v_mad_u32_u24 v30, v36, s3, 16
	v_add_u32_e32 v142, v30, v18
	global_load_dwordx4 v[30:33], v[78:79], off offset:128
	v_add_co_u32_e32 v18, vcc, s0, v76
	s_waitcnt lgkmcnt(0)
	s_barrier
	ds_write_b128 v135, v[26:29] offset:18432
	v_addc_co_u32_e32 v19, vcc, 0, v77, vcc
	s_waitcnt vmcnt(0)
	ds_write2_b64 v143, v[30:31], v[32:33] offset0:128 offset1:130
	global_load_dwordx4 v[114:117], v[18:19], off
	global_load_dwordx4 v[118:121], v[78:79], off offset:384
	ds_read_b128 v[34:37], v146
	ds_read_b128 v[38:41], v146 offset:32
	v_mov_b64_e32 v[132:133], s[94:95]
	v_mov_b64_e32 v[130:131], s[92:93]
	s_waitcnt lgkmcnt(1)
	v_mfma_f32_32x32x16_bf16 v[18:33], v[34:37], v[98:101], v[2:17]
	ds_read_b128 v[34:37], v146 offset:64
	ds_read_b128 v[50:53], v146 offset:4608
	s_waitcnt lgkmcnt(2)
	v_mfma_f32_32x32x16_bf16 v[18:33], v[38:41], v[102:105], v[18:33]
	s_waitcnt lgkmcnt(1)
	v_mfma_f32_32x32x16_bf16 v[18:33], v[34:37], v[106:109], v[18:33]
	ds_read_b128 v[34:37], v146 offset:96
	s_waitcnt lgkmcnt(0)
	v_mfma_f32_32x32x16_bf16 v[18:33], v[34:37], v[110:113], v[18:33]
	v_mfma_f32_32x32x16_bf16 v[34:49], v[50:53], v[98:101], v[2:17]
	ds_read_b128 v[50:53], v146 offset:4640
	s_nop 9
	v_exp_f32_e32 v18, v18
	v_exp_f32_e32 v19, v19
	v_exp_f32_e32 v20, v20
	v_exp_f32_e32 v21, v21
	v_exp_f32_e32 v22, v22
	v_exp_f32_e32 v23, v23
	s_waitcnt lgkmcnt(0)
	v_mfma_f32_32x32x16_bf16 v[34:49], v[50:53], v[102:105], v[34:49]
	ds_read_b128 v[50:53], v146 offset:4672
	v_exp_f32_e32 v24, v24
	v_exp_f32_e32 v25, v25
	v_cvt_pk_bf16_f32 v18, v18, v19
	v_cvt_pk_bf16_f32 v19, v20, v21
	v_cvt_pk_bf16_f32 v20, v22, v23
	v_cvt_pk_bf16_f32 v21, v24, v25
	s_waitcnt lgkmcnt(0)
	v_mfma_f32_32x32x16_bf16 v[34:49], v[50:53], v[106:109], v[34:49]
	ds_read_b128 v[50:53], v146 offset:4704
	ds_read_b128 v[22:25], v142 offset:9216
	ds_read_b128 v[78:81], v142 offset:9248
	v_exp_f32_e32 v82, v26
	v_exp_f32_e32 v83, v27
	v_exp_f32_e32 v84, v28
	v_exp_f32_e32 v85, v29
	v_exp_f32_e32 v122, v30
	s_waitcnt lgkmcnt(2)
; DI void attn_item(const Params& p, int layer, int item, char* smem) {
;     ...
;       const char* sK = smem + bufsel * KV_B;
;       const char* sV = sK + KT_B;
;       f32x16 S[2];
; #pragma unroll
;       for (int kt = 0; kt < 2; ++kt) {
; #pragma unroll
;         for (int s = 0; s < 4; ++s) {
;           bf16x8 kf = *(const bf16x8*)(sK + (kt * 32 + l32) * KROW + s * 32 + h * 16);
;           S[kt] = MFMA32(kf, qf[s], s == 0 ? cinit : S[kt]);
;         }
;       }
;       if (tile < 64 && maskmode == 1) {
;         int qr = tq >> 6, qc = tq & 63;
;         int ws = min(max(qc - 8, 0), 48);
;         int dr = tile - qr + 7;
; #pragma unroll
;         for (int kt = 0; kt < 2; ++kt)
; #pragma unroll
;           for (int r = 0; r < 16; ++r) {
;             int kc = kt * 32 + crow(r, h);
;             bool ok = (unsigned)(kc - ws) < 16u;
;             int bi = ok ? (dr * 31 + kc - qc + 15) : 0;
;             float bv = s_rpb[bi];
;             S[kt][r] = ok ? (S[kt][r] + bv) : -INFINITY;
;           }
;       } else if (tile < 64 && maskmode == 2) {
; #pragma unroll
;         for (int kt = 0; kt < 2; ++kt)
; #pragma unroll
;           for (int r = 0; r < 16; ++r) {
;             int tk = tile * 64 + kt * 32 + crow(r, h);
;             int dd = tq - tk;
;             bool ok = (dd <= 128) && (dd >= -128);
;             S[kt][r] = ok ? S[kt][r] : -INFINITY;
;           }
;       }
; #pragma unroll
;       for (int r = 0; r < 16; ++r) {
;         S[0][r] = __builtin_amdgcn_exp2f(S[0][r]);
;         S[1][r] = __builtin_amdgcn_exp2f(S[1][r]);
;       }
; #pragma unroll
;       for (int kt = 0; kt < 2; ++kt)
; #pragma unroll
;         for (int s2 = 0; s2 < 2; ++s2) {
;           uint4 pw;
;           pw.x = pack_bf16(S[kt][8 * s2 + 0], S[kt][8 * s2 + 1]);
;           pw.y = pack_bf16(S[kt][8 * s2 + 2], S[kt][8 * s2 + 3]);
;           pw.z = pack_bf16(S[kt][8 * s2 + 4], S[kt][8 * s2 + 5]);
;           pw.w = pack_bf16(S[kt][8 * s2 + 6], S[kt][8 * s2 + 7]);
;           bf16x8 pf = __builtin_bit_cast(bf16x8, pw);
;           const int koff = (kt * 32 + 16 * s2 + 8 * h) * 2;
;           {
;             bf16x8 vf = *(const bf16x8*)(sV + l32 * VROW + koff);
;             o0 = MFMA32(vf, pf, o0);
;             lacc = MFMA32(ones, pf, lacc);
;           }
;           {
;             bf16x8 vf = *(const bf16x8*)(sV + (32 + l32) * VROW + koff);
	v_mfma_f32_32x32x16_bf16 v[34:49], v[50:53], v[110:113], v[34:49]
	v_exp_f32_e32 v124, v31
	v_exp_f32_e32 v126, v32
	v_exp_f32_e32 v128, v33
	v_cvt_pk_bf16_f32 v82, v82, v83
	v_cvt_pk_bf16_f32 v83, v84, v85
	v_cvt_pk_bf16_f32 v84, v122, v124
	v_cvt_pk_bf16_f32 v85, v126, v128
	s_nop 4
	v_exp_f32_e32 v86, v34
	v_exp_f32_e32 v87, v35
	v_exp_f32_e32 v88, v36
	v_exp_f32_e32 v89, v37
	v_exp_f32_e32 v90, v38
	v_exp_f32_e32 v91, v39
	v_exp_f32_e32 v92, v40
	v_exp_f32_e32 v93, v41
	v_exp_f32_e32 v94, v42
	v_exp_f32_e32 v95, v43
	v_exp_f32_e32 v96, v44
	v_exp_f32_e32 v97, v45
	v_exp_f32_e32 v123, v46
	v_exp_f32_e32 v125, v47
	v_exp_f32_e32 v127, v48
	v_exp_f32_e32 v129, v49
	s_waitcnt lgkmcnt(1)
	v_mfma_f32_32x32x16_bf16 v[34:49], v[22:25], v[18:21], 0
	ds_read_b128 v[22:25], v142 offset:13824
	s_waitcnt lgkmcnt(1)
	v_mfma_f32_32x32x16_bf16 v[34:49], v[78:81], v[82:85], v[34:49]
	ds_read_b128 v[78:81], v142 offset:13856
	v_mfma_f32_32x32x16_bf16 v[50:65], v[130:133], v[18:21], 0
	s_waitcnt lgkmcnt(1)
	v_mfma_f32_32x32x16_bf16 v[18:33], v[22:25], v[18:21], 0
	v_mfma_f32_32x32x16_bf16 v[50:65], v[130:133], v[82:85], v[50:65]
	s_waitcnt lgkmcnt(0)
	v_mfma_f32_32x32x16_bf16 v[18:33], v[78:81], v[82:85], v[18:33]
	ds_read_b128 v[82:85], v142 offset:9280
	v_cvt_pk_bf16_f32 v78, v86, v87
	v_cvt_pk_bf16_f32 v79, v88, v89
	v_cvt_pk_bf16_f32 v80, v90, v91
	v_cvt_pk_bf16_f32 v81, v92, v93
	s_waitcnt lgkmcnt(0)
	s_nop 0
	v_mfma_f32_32x32x16_bf16 v[34:49], v[82:85], v[78:81], v[34:49]
	ds_read_b128 v[82:85], v142 offset:13888
	s_waitcnt lgkmcnt(0)
	v_mfma_f32_32x32x16_bf16 v[18:33], v[82:85], v[78:81], v[18:33]
	ds_read_b128 v[82:85], v142 offset:9312
	v_mfma_f32_32x32x16_bf16 v[50:65], v[130:133], v[78:81], v[50:65]
	v_cvt_pk_bf16_f32 v78, v94, v95
	v_cvt_pk_bf16_f32 v79, v96, v97
	v_cvt_pk_bf16_f32 v80, v123, v125
	v_cvt_pk_bf16_f32 v81, v127, v129
	s_waitcnt lgkmcnt(0)
	s_nop 0
	v_mfma_f32_32x32x16_bf16 v[34:49], v[82:85], v[78:81], v[34:49]
	ds_read_b128 v[82:85], v142 offset:13920
	s_waitcnt lgkmcnt(0)
	s_barrier
	ds_write_b128 v135, v[66:69]
	ds_write2_b64 v141, v[70:71], v[72:73] offset0:128 offset1:130
	global_load_dwordx4 v[122:125], v[76:77], off
	global_load_dwordx4 v[126:129], v[74:75], off
	v_mfma_f32_32x32x16_bf16 v[50:65], v[130:133], v[78:81], v[50:65]
	v_mfma_f32_32x32x16_bf16 v[18:33], v[82:85], v[78:81], v[18:33]
	ds_read_b128 v[82:85], v146 offset:18432
	ds_read_b128 v[86:89], v146 offset:18464
	s_mov_b32 s2, 2
	v_add_u32_e32 v144, v144, v145
	s_waitcnt lgkmcnt(1)
	v_mfma_f32_32x32x16_bf16 v[66:81], v[82:85], v[98:101], v[2:17]
	ds_read_b128 v[82:85], v146 offset:18496
	ds_read_b128 v[148:151], v146 offset:23040
	s_waitcnt lgkmcnt(2)
	v_mfma_f32_32x32x16_bf16 v[66:81], v[86:89], v[102:105], v[66:81]
	s_waitcnt lgkmcnt(1)
	v_mfma_f32_32x32x16_bf16 v[66:81], v[82:85], v[106:109], v[66:81]
	ds_read_b128 v[82:85], v146 offset:18528
	s_waitcnt lgkmcnt(0)
	v_mfma_f32_32x32x16_bf16 v[66:81], v[82:85], v[110:113], v[66:81]
	v_mfma_f32_32x32x16_bf16 v[82:97], v[148:151], v[98:101], v[2:17]
	ds_read_b128 v[148:151], v146 offset:23072
	s_nop 9
	v_exp_f32_e32 v66, v66
	v_exp_f32_e32 v67, v67
	v_exp_f32_e32 v68, v68
	v_exp_f32_e32 v69, v69
	v_exp_f32_e32 v70, v70
	v_exp_f32_e32 v71, v71
	s_waitcnt lgkmcnt(0)
	v_mfma_f32_32x32x16_bf16 v[82:97], v[148:151], v[102:105], v[82:97]
	ds_read_b128 v[148:151], v146 offset:23104
	v_exp_f32_e32 v72, v72
	v_exp_f32_e32 v73, v73
	v_cvt_pk_bf16_f32 v66, v66, v67
	v_cvt_pk_bf16_f32 v67, v68, v69
	v_cvt_pk_bf16_f32 v68, v70, v71
	v_cvt_pk_bf16_f32 v69, v72, v73
	s_waitcnt lgkmcnt(0)
	v_mfma_f32_32x32x16_bf16 v[82:97], v[148:151], v[106:109], v[82:97]
	ds_read_b128 v[146:149], v146 offset:23136
	v_exp_f32_e32 v78, v78
	v_exp_f32_e32 v79, v79
	v_exp_f32_e32 v80, v80
	v_exp_f32_e32 v81, v81
	s_waitcnt lgkmcnt(0)
	v_mfma_f32_32x32x16_bf16 v[82:97], v[146:149], v[110:113], v[82:97]
	v_exp_f32_e32 v146, v74
	v_exp_f32_e32 v147, v75
	v_exp_f32_e32 v148, v76
	v_exp_f32_e32 v149, v77
	ds_read_b128 v[70:73], v142 offset:27648
	ds_read_b128 v[74:77], v142 offset:27680
	s_nop 5
	v_exp_f32_e32 v82, v82
	s_waitcnt lgkmcnt(1)
	v_mfma_f32_32x32x16_bf16 v[34:49], v[70:73], v[66:69], v[34:49]
	ds_read_b128 v[70:73], v142 offset:32256
	v_exp_f32_e32 v83, v83
	v_exp_f32_e32 v84, v84
	v_exp_f32_e32 v85, v85
	v_exp_f32_e32 v86, v86
	v_exp_f32_e32 v87, v87
	v_exp_f32_e32 v88, v88
	s_waitcnt lgkmcnt(0)
	v_mfma_f32_32x32x16_bf16 v[18:33], v[70:73], v[66:69], v[18:33]
	ds_read_b128 v[70:73], v142 offset:32288
	v_exp_f32_e32 v89, v89
	v_exp_f32_e32 v90, v90
	v_exp_f32_e32 v91, v91
	v_exp_f32_e32 v92, v92
	v_exp_f32_e32 v93, v93
	v_exp_f32_e32 v94, v94
	v_mfma_f32_32x32x16_bf16 v[50:65], v[130:133], v[66:69], v[50:65]
	v_cvt_pk_bf16_f32 v66, v146, v147
	v_cvt_pk_bf16_f32 v67, v148, v149
	v_cvt_pk_bf16_f32 v68, v78, v79
	v_cvt_pk_bf16_f32 v69, v80, v81
	v_exp_f32_e32 v95, v95
	v_exp_f32_e32 v96, v96
	v_exp_f32_e32 v97, v97
	s_waitcnt lgkmcnt(0)
	v_mfma_f32_32x32x16_bf16 v[18:33], v[70:73], v[66:69], v[18:33]
	ds_read_b128 v[70:73], v142 offset:27712
	v_mfma_f32_32x32x16_bf16 v[34:49], v[74:77], v[66:69], v[34:49]
	v_mfma_f32_32x32x16_bf16 v[50:65], v[130:133], v[66:69], v[50:65]
	v_cvt_pk_bf16_f32 v66, v82, v83
	v_cvt_pk_bf16_f32 v67, v84, v85
	v_cvt_pk_bf16_f32 v68, v86, v87
	v_cvt_pk_bf16_f32 v69, v88, v89
	s_waitcnt lgkmcnt(0)
	s_nop 0
	v_mfma_f32_32x32x16_bf16 v[34:49], v[70:73], v[66:69], v[34:49]
	ds_read_b128 v[70:73], v142 offset:32320
	s_waitcnt lgkmcnt(0)
	v_mfma_f32_32x32x16_bf16 v[18:33], v[70:73], v[66:69], v[18:33]
	ds_read_b128 v[70:73], v142 offset:27744
	v_mfma_f32_32x32x16_bf16 v[50:65], v[130:133], v[66:69], v[50:65]
	v_cvt_pk_bf16_f32 v66, v90, v91
	v_cvt_pk_bf16_f32 v67, v92, v93
	v_cvt_pk_bf16_f32 v68, v94, v95
	v_cvt_pk_bf16_f32 v69, v96, v97
	s_waitcnt lgkmcnt(0)
	s_nop 0
	v_mfma_f32_32x32x16_bf16 v[34:49], v[70:73], v[66:69], v[34:49]
	ds_read_b128 v[70:73], v142 offset:32352
	s_waitcnt lgkmcnt(0)
	s_barrier
	v_mfma_f32_32x32x16_bf16 v[50:65], v[130:133], v[66:69], v[50:65]
	v_mfma_f32_32x32x16_bf16 v[18:33], v[70:73], v[66:69], v[18:33]
	s_nop 11
	v_mov_b32_e32 v51, 0
	v_mov_b32_e32 v52, 0
	v_lshl_add_u64 v[132:133], v[136:137], 0, v[0:1]
	v_lshl_add_u64 v[130:131], v[138:139], 0, v[0:1]
	s_nop 0
	v_readfirstlane_b32 s92, v132
	v_readfirstlane_b32 s93, v133
	v_readfirstlane_b32 s94, v130
	v_readfirstlane_b32 s95, v131
	s_nop 3
	v_subrev_u32_e32 v53, s92, v132
	v_subrev_u32_e32 v54, s94, v130
	s_add_u32 s92, s92, 0x2000
	s_addc_u32 s93, s93, 0
	s_branch .LBB0_261
	.p2align	6

; #define PG8_STAGE(bufoff, gbase, voff) do { _Pragma("unroll") for (int _i = 0; _i < 2; ++_i) \
;     __builtin_amdgcn_global_load_lds((const unsigned*)((const char*)(gbase) + (voff)[_i]), (LAS unsigned*)(lds + (bufoff) + ldsw + _i * 8192), 16, 0, 0); } while (0)
; #define PG8_WAIT_V(n) asm volatile("s_waitcnt vmcnt(" #n ")" ::: "memory")
; #define PG8_BAR __builtin_amdgcn_s_barrier()
; template <class Epi, class Sched>
; DI void gemm_phase(LAS unsigned char* lds, const Gemm g, const Sched& S, const Epi& E) {
;     ...
;   f32x4 acc[2][2][4][2];
; #pragma unroll
;   for (int a = 0; a < 2; ++a)
; #pragma unroll
;     for (int b = 0; b < 2; ++b)
; #pragma unroll
;       for (int m = 0; m < 4; ++m)
; #pragma unroll
;         for (int n = 0; n < 2; ++n) acc[a][b][m][n] = (f32x4){0.f, 0.f, 0.f, 0.f};
;     ...
;   PG8_STAGE(PG8_SB(0, 0), cB, voffB); PG8_STAGE(PG8_SA(0, 0), cA, voffA); PG8_STAGE(PG8_SB(0, 1), cB + hstepB, voffB); PG8_STAGE(PG8_SA(0, 1), cA + hstep, voffA);
;   if (wr == 1) PG8_BAR;
;   PG8_WAIT_V(4); PG8_BAR;
;   PG8_STAGE(PG8_SB(1, 0), cB + kstep, voffB); PG8_STAGE(PG8_SA(1, 0), cA + kstep, voffA); PG8_STAGE(PG8_SB(1, 1), cB + hstepB + kstep, voffB);
;   PG8_WAIT_V(6); PG8_BAR;
.LBB0_489:
	v_lshl_add_u64 v[4:5], s[2:3], 0, v[0:1]
	v_mov_b32_e32 v127, v1
	v_lshl_add_u64 v[6:7], s[2:3], 0, v[126:127]
	v_and_b32_e32 v128, 15, v2
	v_bfe_u32 v132, v2, 4, 2
	s_add_i32 m0, s18, 0x18000
	v_lshl_add_u64 v[2:3], v[4:5], 0, s[70:71]
	v_lshl_add_u64 v[8:9], s[4:5], 0, v[0:1]
	s_waitcnt vmcnt(4)
	s_barrier
	global_load_lds_dwordx4 v[2:3], off
	v_lshl_add_u64 v[2:3], v[6:7], 0, s[70:71]
	s_add_i32 m0, s18, 0x1a000
	s_add_i32 s22, s18, 0x8000
	v_lshl_add_u64 v[10:11], s[4:5], 0, v[126:127]
	global_load_lds_dwordx4 v[2:3], off
	v_lshl_add_u64 v[2:3], v[8:9], 0, s[70:71]
	s_mov_b32 m0, s22
	s_add_i32 s23, s18, 0xa000
	v_lshl_add_u64 v[12:13], s[8:9], 0, v[0:1]
	global_load_lds_dwordx4 v[2:3], off
	v_lshl_add_u64 v[2:3], v[10:11], 0, s[70:71]
	s_mov_b32 m0, s23
	v_lshl_add_u64 v[14:15], s[8:9], 0, v[126:127]
	global_load_lds_dwordx4 v[2:3], off
	s_add_i32 m0, s18, 0x1c000
	v_lshl_add_u64 v[2:3], v[12:13], 0, s[70:71]
	global_load_lds_dwordx4 v[2:3], off
	v_lshl_add_u64 v[2:3], v[14:15], 0, s[70:71]
	s_add_i32 m0, s18, 0x1e000
	s_lshl_b32 s8, s11, 5
	global_load_lds_dwordx4 v[2:3], off
	s_waitcnt vmcnt(6)
	s_and_b32 s16, s8, 0x60
	v_mov_b32_e32 v137, 0
	v_lshl_or_b32 v146, s10, 6, v128
	s_cmp_lt_i32 s6, 64
	v_mov_b32_e32 v136, v137
	v_mov_b32_e32 v135, v137
	v_mov_b32_e32 v134, v137
	v_mov_b32_e32 v125, v137
	v_mov_b32_e32 v124, v137
	v_mov_b32_e32 v123, v137
	v_mov_b32_e32 v122, v137
	v_mov_b32_e32 v113, v137
	v_mov_b32_e32 v112, v137
	v_mov_b32_e32 v111, v137
	v_mov_b32_e32 v110, v137
	v_mov_b32_e32 v109, v137
	v_mov_b32_e32 v108, v137
	v_mov_b32_e32 v107, v137
	v_mov_b32_e32 v106, v137
	v_mov_b32_e32 v97, v137
	v_mov_b32_e32 v96, v137
	v_mov_b32_e32 v95, v137
	v_mov_b32_e32 v94, v137
	v_mov_b32_e32 v93, v137
	v_mov_b32_e32 v92, v137
	v_mov_b32_e32 v91, v137
	v_mov_b32_e32 v90, v137
	v_mov_b32_e32 v81, v137
	v_mov_b32_e32 v80, v137
	v_mov_b32_e32 v79, v137
	v_mov_b32_e32 v78, v137
	v_mov_b32_e32 v77, v137
	v_mov_b32_e32 v76, v137
	v_mov_b32_e32 v75, v137
	v_mov_b32_e32 v74, v137
	v_mov_b32_e32 v121, v137
	v_mov_b32_e32 v120, v137
	v_mov_b32_e32 v119, v137
	v_mov_b32_e32 v118, v137
	v_mov_b32_e32 v117, v137
	v_mov_b32_e32 v116, v137
	v_mov_b32_e32 v115, v137
	v_mov_b32_e32 v114, v137
	v_mov_b32_e32 v105, v137
	v_mov_b32_e32 v104, v137
	v_mov_b32_e32 v103, v137
	v_mov_b32_e32 v102, v137
	v_mov_b32_e32 v101, v137
	v_mov_b32_e32 v100, v137
	v_mov_b32_e32 v99, v137
	v_mov_b32_e32 v98, v137
	v_mov_b32_e32 v89, v137
	v_mov_b32_e32 v88, v137
	v_mov_b32_e32 v87, v137
	v_mov_b32_e32 v86, v137
	v_mov_b32_e32 v85, v137
	v_mov_b32_e32 v84, v137
	v_mov_b32_e32 v83, v137
	v_mov_b32_e32 v82, v137
	v_mov_b32_e32 v73, v137
	v_mov_b32_e32 v72, v137
	v_mov_b32_e32 v71, v137
	v_mov_b32_e32 v70, v137
	v_mov_b32_e32 v69, v137
	v_mov_b32_e32 v68, v137
	v_mov_b32_e32 v67, v137
	v_mov_b32_e32 v66, v137
	v_mov_b32_e32 v65, v137
	v_mov_b32_e32 v64, v137
	v_mov_b32_e32 v63, v137
	v_mov_b32_e32 v62, v137
	v_mov_b32_e32 v61, v137
	v_mov_b32_e32 v60, v137
	v_mov_b32_e32 v59, v137
	v_mov_b32_e32 v58, v137
	v_mov_b32_e32 v53, v137
	v_mov_b32_e32 v52, v137
	v_mov_b32_e32 v51, v137
	v_mov_b32_e32 v50, v137
	v_mov_b32_e32 v45, v137
	v_mov_b32_e32 v44, v137
	v_mov_b32_e32 v43, v137
	v_mov_b32_e32 v42, v137
	v_mov_b32_e32 v37, v137
	v_mov_b32_e32 v36, v137
	v_mov_b32_e32 v35, v137
	v_mov_b32_e32 v34, v137
	v_mov_b32_e32 v29, v137
	v_mov_b32_e32 v28, v137
	v_mov_b32_e32 v27, v137
	v_mov_b32_e32 v26, v137
	v_mov_b32_e32 v21, v137
	v_mov_b32_e32 v20, v137
	v_mov_b32_e32 v19, v137
	v_mov_b32_e32 v18, v137
	v_mov_b32_e32 v13, v137
	v_mov_b32_e32 v12, v137
	v_mov_b32_e32 v11, v137
	v_mov_b32_e32 v10, v137
	v_mov_b32_e32 v57, v137
	v_mov_b32_e32 v56, v137
	v_mov_b32_e32 v55, v137
	v_mov_b32_e32 v54, v137
	v_mov_b32_e32 v49, v137
	v_mov_b32_e32 v48, v137
	v_mov_b32_e32 v47, v137
	v_mov_b32_e32 v46, v137
	v_mov_b32_e32 v41, v137
	v_mov_b32_e32 v40, v137
	v_mov_b32_e32 v39, v137
	v_mov_b32_e32 v38, v137
	v_mov_b32_e32 v33, v137
	v_mov_b32_e32 v32, v137
	v_mov_b32_e32 v31, v137
	v_mov_b32_e32 v30, v137
	v_mov_b32_e32 v25, v137
	v_mov_b32_e32 v24, v137
	v_mov_b32_e32 v23, v137
	v_mov_b32_e32 v22, v137
	v_mov_b32_e32 v17, v137
	v_mov_b32_e32 v16, v137
	v_mov_b32_e32 v15, v137
	v_mov_b32_e32 v14, v137
	v_mov_b32_e32 v9, v137
	v_mov_b32_e32 v8, v137
	v_mov_b32_e32 v7, v137
	v_mov_b32_e32 v6, v137
	v_mov_b32_e32 v5, v137
	v_mov_b32_e32 v4, v137
	v_mov_b32_e32 v3, v137
	v_mov_b32_e32 v2, v137
	s_barrier
;   DI bool next(int i, Unit& o) const { if (i != 0 || !valid) return false; o = u; return true; }
; template <class Epi, class Sched>
; DI void gemm_phase(LAS unsigned char* lds, const Gemm g, const Sched& S, const Epi& E) {
;     ...
;     voffA[i] = (unsigned)(R * K + C) * 2u; voffB[i] = (unsigned)(Rb * K + C) * 2u;
;   }
;   const size_t kstep = (size_t)(BK * 2);
;   const size_t hstep = (size_t)HALF * K * 2;
;   const size_t hstepB = (Epi::BMAP == 2) ? (size_t)32 * K * 2 : hstep;
;   const size_t tstep = 2 * hstep;
;   const unsigned ldsw = (unsigned)wid * 1024u;
;   const int aoff = lds_byte(wr * 64 + fr, fq * 8), boff = lds_byte(wc * 32 + fr, fq * 8);
;     ...
;   Unit cur, nxt; int ui = 0;
;   if (!S.next(0, cur)) return;
;   f32x4 acc[2][2][4][2];
; #pragma unroll
;   for (int a = 0; a < 2; ++a)
; #pragma unroll
;     for (int b = 0; b < 2; ++b)
; #pragma unroll
;       for (int m = 0; m < 4; ++m)
; #pragma unroll
;         for (int n = 0; n < 2; ++n) acc[a][b][m][n] = (f32x4){0.f, 0.f, 0.f, 0.f};
	s_cbranch_scc1 .LBB0_493
	s_lshr_b32 s7, s7, 26
	s_add_i32 s7, s6, s7
	s_ashr_i32 s24, s7, 6
	v_lshlrev_b32_e32 v2, 4, v132
	v_lshlrev_b32_e32 v3, 6, v146
	s_movk_i32 s7, 0x3c0
	v_lshlrev_b32_e32 v4, 2, v146
	v_and_or_b32 v3, v3, s7, v2
	s_lshl_b32 s7, s10, 13
	v_and_b32_e32 v4, 32, v4
	v_bitop3_b32 v3, v3, s7, v4 bitop3:0xde
	v_lshlrev_b32_e32 v4, 2, v128
	v_lshl_or_b32 v2, v128, 6, v2
	s_lshl_b32 s7, s16, 7
	v_and_b32_e32 v4, 32, v4
	v_bitop3_b32 v133, v2, s7, v4 bitop3:0xde
	s_lshl_b32 s7, s13, 9
	s_bitset1_b32 s7, 8
	s_add_i32 s25, s24, -2
	s_mul_hi_i32 s8, s7, s6
	s_mul_i32 s7, s7, s6
	s_add_u32 s6, s90, s7
	s_addc_u32 s7, s91, s8
	v_mov_b32_e32 v2, 0
	v_lshl_add_u64 v[128:129], s[6:7], 0, v[0:1]
	v_lshl_add_u64 v[130:131], s[6:7], 0, v[126:127]
	s_mov_b32 s8, 0
	s_mov_b64 s[6:7], 0x2000080
	v_add_u32_e32 v138, 16, v3
	v_mov_b32_e32 v3, v2
	v_mov_b32_e32 v4, v2
	v_mov_b32_e32 v5, v2
	v_mov_b32_e32 v6, v2
	v_mov_b32_e32 v7, v2
	v_mov_b32_e32 v8, v2
	v_mov_b32_e32 v9, v2
	v_mov_b32_e32 v14, v2
	v_mov_b32_e32 v15, v2
	v_mov_b32_e32 v16, v2
	v_mov_b32_e32 v17, v2
	v_mov_b32_e32 v22, v2
	v_mov_b32_e32 v23, v2
	v_mov_b32_e32 v24, v2
	v_mov_b32_e32 v25, v2
	v_mov_b32_e32 v30, v2
	v_mov_b32_e32 v31, v2
	v_mov_b32_e32 v32, v2
	v_mov_b32_e32 v33, v2
	v_mov_b32_e32 v38, v2
	v_mov_b32_e32 v39, v2
	v_mov_b32_e32 v40, v2
	v_mov_b32_e32 v41, v2
	v_mov_b32_e32 v46, v2
	v_mov_b32_e32 v47, v2
	v_mov_b32_e32 v48, v2
	v_mov_b32_e32 v49, v2
	v_mov_b32_e32 v54, v2
	v_mov_b32_e32 v55, v2
	v_mov_b32_e32 v56, v2
	v_mov_b32_e32 v57, v2
	v_mov_b32_e32 v10, v2
	v_mov_b32_e32 v11, v2
	v_mov_b32_e32 v12, v2
	v_mov_b32_e32 v13, v2
	v_mov_b32_e32 v18, v2
	v_mov_b32_e32 v19, v2
	v_mov_b32_e32 v20, v2
	v_mov_b32_e32 v21, v2
	v_mov_b32_e32 v26, v2
	v_mov_b32_e32 v27, v2
	v_mov_b32_e32 v28, v2
	v_mov_b32_e32 v29, v2
	v_mov_b32_e32 v34, v2
	v_mov_b32_e32 v35, v2
	v_mov_b32_e32 v36, v2
	v_mov_b32_e32 v37, v2
	v_mov_b32_e32 v42, v2
	v_mov_b32_e32 v43, v2
	v_mov_b32_e32 v44, v2
	v_mov_b32_e32 v45, v2
	v_mov_b32_e32 v50, v2
	v_mov_b32_e32 v51, v2
	v_mov_b32_e32 v52, v2
	v_mov_b32_e32 v53, v2
	v_mov_b32_e32 v58, v2
	v_mov_b32_e32 v59, v2
	v_mov_b32_e32 v60, v2
	v_mov_b32_e32 v61, v2
	v_mov_b32_e32 v62, v2
	v_mov_b32_e32 v63, v2
	v_mov_b32_e32 v64, v2
	v_mov_b32_e32 v65, v2
	v_mov_b32_e32 v66, v2
	v_mov_b32_e32 v67, v2
	v_mov_b32_e32 v68, v2
	v_mov_b32_e32 v69, v2
	v_mov_b32_e32 v70, v2
	v_mov_b32_e32 v71, v2
	v_mov_b32_e32 v72, v2
	v_mov_b32_e32 v73, v2
	v_mov_b32_e32 v82, v2
	v_mov_b32_e32 v83, v2
	v_mov_b32_e32 v84, v2
	v_mov_b32_e32 v85, v2
	v_mov_b32_e32 v86, v2
	v_mov_b32_e32 v87, v2
	v_mov_b32_e32 v88, v2
	v_mov_b32_e32 v89, v2
	v_mov_b32_e32 v98, v2
	v_mov_b32_e32 v99, v2
	v_mov_b32_e32 v100, v2
	v_mov_b32_e32 v101, v2
	v_mov_b32_e32 v102, v2
	v_mov_b32_e32 v103, v2
	v_mov_b32_e32 v104, v2
	v_mov_b32_e32 v105, v2
	v_mov_b32_e32 v114, v2
	v_mov_b32_e32 v115, v2
	v_mov_b32_e32 v116, v2
	v_mov_b32_e32 v117, v2
	v_mov_b32_e32 v118, v2
	v_mov_b32_e32 v119, v2
	v_mov_b32_e32 v120, v2
	v_mov_b32_e32 v121, v2
	v_mov_b32_e32 v74, v2
	v_mov_b32_e32 v75, v2
	v_mov_b32_e32 v76, v2
	v_mov_b32_e32 v77, v2
	v_mov_b32_e32 v78, v2
	v_mov_b32_e32 v79, v2
	v_mov_b32_e32 v80, v2
	v_mov_b32_e32 v81, v2
	v_mov_b32_e32 v90, v2
	v_mov_b32_e32 v91, v2
	v_mov_b32_e32 v92, v2
	v_mov_b32_e32 v93, v2
	v_mov_b32_e32 v94, v2
	v_mov_b32_e32 v95, v2
	v_mov_b32_e32 v96, v2
	v_mov_b32_e32 v97, v2
	v_mov_b32_e32 v106, v2
	v_mov_b32_e32 v107, v2
	v_mov_b32_e32 v108, v2
	v_mov_b32_e32 v109, v2
	v_mov_b32_e32 v110, v2
	v_mov_b32_e32 v111, v2
	v_mov_b32_e32 v112, v2
	v_mov_b32_e32 v113, v2
	v_mov_b32_e32 v122, v2
	v_mov_b32_e32 v123, v2
	v_mov_b32_e32 v124, v2
	v_mov_b32_e32 v125, v2
	v_mov_b32_e32 v134, v2
	v_mov_b32_e32 v135, v2
	v_mov_b32_e32 v136, v2
	v_mov_b32_e32 v137, v2
	s_waitcnt vmcnt(0)
	.p2align	6

;   DI bool next(int i, Unit& o) const { if (i != 0 || !valid) return false; o = u; return true; }
; template <class Epi, class Sched>
; DI void gemm_phase(LAS unsigned char* lds, const Gemm g, const Sched& S, const Epi& E) {
;     ...
;   for (;;) {
;     const bool has_next = S.next(ui + 1, nxt);
;     const char* nA = has_next ? (const char*)g.A + (size_t)nxt.pm * tstep : cA; const char* nB = has_next ? (const char*)g.Bt + (size_t)nxt.pn * tstep : cB;
;     for (int t = 0; t < nt; t += 2) {
;     ...
;     E(acc, cur, wr, wc, fr, fq);
;     if (!has_next) break;
; #pragma unroll
;     for (int a = 0; a < 2; ++a)
; #pragma unroll
;       for (int b = 0; b < 2; ++b)
; #pragma unroll
;         for (int m = 0; m < 4; ++m)
; #pragma unroll
;           for (int n = 0; n < 2; ++n) acc[a][b][m][n] = (f32x4){0.f, 0.f, 0.f, 0.f};
;     cur = nxt; cA = nA; cB = nB; ++ui;
.LBB0_517:
	v_mov_b32_e32 v177, 0
	s_andn2_b64 vcc, exec, s[18:19]
	v_mov_b32_e32 v176, v177
	v_mov_b32_e32 v175, v177
	v_mov_b32_e32 v174, v177
	v_mov_b32_e32 v173, v177
	v_mov_b32_e32 v172, v177
	v_mov_b32_e32 v171, v177
	v_mov_b32_e32 v170, v177
	s_waitcnt vmcnt(0)
	v_mov_b32_e32 v161, v177
	v_mov_b32_e32 v160, v177
	v_mov_b32_e32 v159, v177
	v_mov_b32_e32 v158, v177
	v_mov_b32_e32 v157, v177
	v_mov_b32_e32 v156, v177
	v_mov_b32_e32 v155, v177
	v_mov_b32_e32 v154, v177
	v_mov_b32_e32 v145, v177
	v_mov_b32_e32 v144, v177
	v_mov_b32_e32 v143, v177
	v_mov_b32_e32 v142, v177
	v_mov_b32_e32 v141, v177
	v_mov_b32_e32 v140, v177
	v_mov_b32_e32 v139, v177
	v_mov_b32_e32 v138, v177
	v_mov_b32_e32 v113, v177
	v_mov_b32_e32 v112, v177
	v_mov_b32_e32 v111, v177
	v_mov_b32_e32 v110, v177
	v_mov_b32_e32 v109, v177
	v_mov_b32_e32 v108, v177
	v_mov_b32_e32 v107, v177
	v_mov_b32_e32 v106, v177
	v_mov_b32_e32 v169, v177
	v_mov_b32_e32 v168, v177
	v_mov_b32_e32 v167, v177
	v_mov_b32_e32 v166, v177
	v_mov_b32_e32 v165, v177
	v_mov_b32_e32 v164, v177
	v_mov_b32_e32 v163, v177
	v_mov_b32_e32 v162, v177
	v_mov_b32_e32 v153, v177
	v_mov_b32_e32 v152, v177
	v_mov_b32_e32 v151, v177
	v_mov_b32_e32 v150, v177
	v_mov_b32_e32 v149, v177
	v_mov_b32_e32 v148, v177
	v_mov_b32_e32 v147, v177
	v_mov_b32_e32 v146, v177
	v_mov_b32_e32 v137, v177
	v_mov_b32_e32 v136, v177
	v_mov_b32_e32 v135, v177
	v_mov_b32_e32 v134, v177
	v_mov_b32_e32 v133, v177
	v_mov_b32_e32 v132, v177
	v_mov_b32_e32 v131, v177
	v_mov_b32_e32 v130, v177
	v_mov_b32_e32 v105, v177
	v_mov_b32_e32 v104, v177
	v_mov_b32_e32 v103, v177
	v_mov_b32_e32 v102, v177
	v_mov_b32_e32 v93, v177
	v_mov_b32_e32 v92, v177
	v_mov_b32_e32 v91, v177
	v_mov_b32_e32 v90, v177
	v_mov_b32_e32 v65, v177
	v_mov_b32_e32 v64, v177
	v_mov_b32_e32 v63, v177
	v_mov_b32_e32 v62, v177
	v_mov_b32_e32 v61, v177
	v_mov_b32_e32 v60, v177
	v_mov_b32_e32 v59, v177
	v_mov_b32_e32 v58, v177
	v_mov_b32_e32 v49, v177
	v_mov_b32_e32 v48, v177
	v_mov_b32_e32 v47, v177
	v_mov_b32_e32 v46, v177
	v_mov_b32_e32 v45, v177
	v_mov_b32_e32 v44, v177
	v_mov_b32_e32 v43, v177
	v_mov_b32_e32 v42, v177
	v_mov_b32_e32 v33, v177
	v_mov_b32_e32 v32, v177
	v_mov_b32_e32 v31, v177
	v_mov_b32_e32 v30, v177
	v_mov_b32_e32 v29, v177
	v_mov_b32_e32 v28, v177
	v_mov_b32_e32 v27, v177
	v_mov_b32_e32 v26, v177
	v_mov_b32_e32 v17, v177
	v_mov_b32_e32 v16, v177
	v_mov_b32_e32 v15, v177
	v_mov_b32_e32 v14, v177
	v_mov_b32_e32 v13, v177
	v_mov_b32_e32 v12, v177
	v_mov_b32_e32 v11, v177
	v_mov_b32_e32 v10, v177
	v_mov_b32_e32 v57, v177
	v_mov_b32_e32 v56, v177
	v_mov_b32_e32 v55, v177
	v_mov_b32_e32 v54, v177
	v_mov_b32_e32 v53, v177
	v_mov_b32_e32 v52, v177
	v_mov_b32_e32 v51, v177
	v_mov_b32_e32 v50, v177
	v_mov_b32_e32 v41, v177
	v_mov_b32_e32 v40, v177
	v_mov_b32_e32 v39, v177
	v_mov_b32_e32 v38, v177
	v_mov_b32_e32 v37, v177
	v_mov_b32_e32 v36, v177
	v_mov_b32_e32 v35, v177
	v_mov_b32_e32 v34, v177
	v_mov_b32_e32 v25, v177
	v_mov_b32_e32 v24, v177
	v_mov_b32_e32 v23, v177
	v_mov_b32_e32 v22, v177
	v_mov_b32_e32 v21, v177
	v_mov_b32_e32 v20, v177
	v_mov_b32_e32 v19, v177
	v_mov_b32_e32 v18, v177
	v_mov_b32_e32 v9, v177
	v_mov_b32_e32 v8, v177
	v_mov_b32_e32 v7, v177
	v_mov_b32_e32 v6, v177
	v_mov_b32_e32 v5, v177
	v_mov_b32_e32 v4, v177
	v_mov_b32_e32 v3, v177
	v_mov_b32_e32 v2, v177
	s_cbranch_vccnz .LBB0_521
	s_add_u32 s2, s2, 0x80
	s_addc_u32 s3, s3, 0
	s_add_u32 s11, s8, 0x100
	v_mov_b32_e32 v2, 0
	v_mov_b32_e32 v200, v184
	v_mov_b32_e32 v201, 0x358637bd
	v_mov_b32_e32 v210, 0x3e38aa3b
	v_mov_b32_e32 v217, 1
	v_mov_b64_e32 v[178:179], 0x200
	s_addc_u32 s22, s9, 0
	s_mov_b32 s6, 0
	v_mov_b32_e32 v3, v2
	v_mov_b32_e32 v4, v2
	v_mov_b32_e32 v5, v2
	v_mov_b32_e32 v6, v2
	v_mov_b32_e32 v7, v2
	v_mov_b32_e32 v8, v2
	v_mov_b32_e32 v9, v2
	v_mov_b32_e32 v18, v2
	v_mov_b32_e32 v19, v2
	v_mov_b32_e32 v20, v2
	v_mov_b32_e32 v21, v2
	v_mov_b32_e32 v22, v2
	v_mov_b32_e32 v23, v2
	v_mov_b32_e32 v24, v2
	v_mov_b32_e32 v25, v2
	v_mov_b32_e32 v34, v2
	v_mov_b32_e32 v35, v2
	v_mov_b32_e32 v36, v2
	v_mov_b32_e32 v37, v2
	v_mov_b32_e32 v38, v2
	v_mov_b32_e32 v39, v2
	v_mov_b32_e32 v40, v2
	v_mov_b32_e32 v41, v2
	v_mov_b32_e32 v50, v2
	v_mov_b32_e32 v51, v2
	v_mov_b32_e32 v52, v2
	v_mov_b32_e32 v53, v2
	v_mov_b32_e32 v54, v2
	v_mov_b32_e32 v55, v2
	v_mov_b32_e32 v56, v2
	v_mov_b32_e32 v57, v2
	v_mov_b32_e32 v10, v2
	v_mov_b32_e32 v11, v2
	v_mov_b32_e32 v12, v2
	v_mov_b32_e32 v13, v2
	v_mov_b32_e32 v14, v2
	v_mov_b32_e32 v15, v2
	v_mov_b32_e32 v16, v2
	v_mov_b32_e32 v17, v2
	v_mov_b32_e32 v26, v2
	v_mov_b32_e32 v27, v2
	v_mov_b32_e32 v28, v2
	v_mov_b32_e32 v29, v2
	v_mov_b32_e32 v30, v2
	v_mov_b32_e32 v31, v2
	v_mov_b32_e32 v32, v2
	v_mov_b32_e32 v33, v2
	v_mov_b32_e32 v42, v2
	v_mov_b32_e32 v43, v2
	v_mov_b32_e32 v44, v2
	v_mov_b32_e32 v45, v2
	v_mov_b32_e32 v46, v2
	v_mov_b32_e32 v47, v2
	v_mov_b32_e32 v48, v2
	v_mov_b32_e32 v49, v2
	v_mov_b32_e32 v58, v2
	v_mov_b32_e32 v59, v2
	v_mov_b32_e32 v60, v2
	v_mov_b32_e32 v61, v2
	v_mov_b32_e32 v62, v2
	v_mov_b32_e32 v63, v2
	v_mov_b32_e32 v64, v2
	v_mov_b32_e32 v65, v2
	v_mov_b32_e32 v90, v2
	v_mov_b32_e32 v91, v2
	v_mov_b32_e32 v92, v2
	v_mov_b32_e32 v93, v2
	v_mov_b32_e32 v102, v2
	v_mov_b32_e32 v103, v2
	v_mov_b32_e32 v104, v2
	v_mov_b32_e32 v105, v2
	v_mov_b32_e32 v130, v2
	v_mov_b32_e32 v131, v2
	v_mov_b32_e32 v132, v2
	v_mov_b32_e32 v133, v2
	v_mov_b32_e32 v134, v2
	v_mov_b32_e32 v135, v2
	v_mov_b32_e32 v136, v2
	v_mov_b32_e32 v137, v2
	v_mov_b32_e32 v146, v2
	v_mov_b32_e32 v147, v2
	v_mov_b32_e32 v148, v2
	v_mov_b32_e32 v149, v2
	v_mov_b32_e32 v150, v2
	v_mov_b32_e32 v151, v2
	v_mov_b32_e32 v152, v2
	v_mov_b32_e32 v153, v2
	v_mov_b32_e32 v162, v2
	v_mov_b32_e32 v163, v2
	v_mov_b32_e32 v164, v2
	v_mov_b32_e32 v165, v2
	v_mov_b32_e32 v166, v2
	v_mov_b32_e32 v167, v2
	v_mov_b32_e32 v168, v2
	v_mov_b32_e32 v169, v2
	v_mov_b32_e32 v106, v2
	v_mov_b32_e32 v107, v2
	v_mov_b32_e32 v108, v2
	v_mov_b32_e32 v109, v2
	v_mov_b32_e32 v110, v2
	v_mov_b32_e32 v111, v2
	v_mov_b32_e32 v112, v2
	v_mov_b32_e32 v113, v2
	v_mov_b32_e32 v138, v2
	v_mov_b32_e32 v139, v2
	v_mov_b32_e32 v140, v2
	v_mov_b32_e32 v141, v2
	v_mov_b32_e32 v142, v2
	v_mov_b32_e32 v143, v2
	v_mov_b32_e32 v144, v2
	v_mov_b32_e32 v145, v2
	v_mov_b32_e32 v154, v2
	v_mov_b32_e32 v155, v2
	v_mov_b32_e32 v156, v2
	v_mov_b32_e32 v157, v2
	v_mov_b32_e32 v158, v2
	v_mov_b32_e32 v159, v2
	v_mov_b32_e32 v160, v2
	v_mov_b32_e32 v161, v2
	v_mov_b32_e32 v170, v2
	v_mov_b32_e32 v171, v2
	v_mov_b32_e32 v172, v2
	v_mov_b32_e32 v173, v2
	v_mov_b32_e32 v174, v2
	v_mov_b32_e32 v175, v2
	v_mov_b32_e32 v176, v2
	v_mov_b32_e32 v177, v2
	.p2align	6

; #define PG8_STAGE(bufoff, gbase, voff) do { _Pragma("unroll") for (int _i = 0; _i < 2; ++_i) \
;     __builtin_amdgcn_global_load_lds((const unsigned*)((const char*)(gbase) + (voff)[_i]), (LAS unsigned*)(lds + (bufoff) + ldsw + _i * 8192), 16, 0, 0); } while (0)
; #define PG8_WAIT_V(n) asm volatile("s_waitcnt vmcnt(" #n ")" ::: "memory")
; #define PG8_BAR __builtin_amdgcn_s_barrier()
; template <class Epi, class Sched>
; DI void gemm_phase(LAS unsigned char* lds, const Gemm g, const Sched& S, const Epi& E) {
;     ...
;   f32x4 acc[2][2][4][2];
; #pragma unroll
;   for (int a = 0; a < 2; ++a)
; #pragma unroll
;     for (int b = 0; b < 2; ++b)
; #pragma unroll
;       for (int m = 0; m < 4; ++m)
; #pragma unroll
;         for (int n = 0; n < 2; ++n) acc[a][b][m][n] = (f32x4){0.f, 0.f, 0.f, 0.f};
;     ...
;   PG8_STAGE(PG8_SB(0, 0), cB, voffB); PG8_STAGE(PG8_SA(0, 0), cA, voffA); PG8_STAGE(PG8_SB(0, 1), cB + hstepB, voffB); PG8_STAGE(PG8_SA(0, 1), cA + hstep, voffA);
;   if (wr == 1) PG8_BAR;
;   PG8_WAIT_V(4); PG8_BAR;
;   PG8_STAGE(PG8_SB(1, 0), cB + kstep, voffB); PG8_STAGE(PG8_SA(1, 0), cA + kstep, voffA); PG8_STAGE(PG8_SB(1, 1), cB + hstepB + kstep, voffB);
;   PG8_WAIT_V(6); PG8_BAR;
.LBB0_829:
	v_lshl_add_u64 v[4:5], s[4:5], 0, v[0:1]
	v_mov_b32_e32 v83, v1
	v_lshl_add_u64 v[6:7], s[4:5], 0, v[82:83]
	v_mov_b32_e32 v87, v1
	v_and_b32_e32 v150, 15, v2
	v_bfe_u32 v148, v2, 4, 2
	s_add_i32 m0, s18, 0x18000
	v_lshl_add_u64 v[2:3], v[4:5], 0, s[70:71]
	v_lshl_add_u64 v[8:9], s[6:7], 0, v[86:87]
	v_mov_b32_e32 v85, v1
	s_waitcnt vmcnt(4)
	s_barrier
	global_load_lds_dwordx4 v[2:3], off
	v_lshl_add_u64 v[2:3], v[6:7], 0, s[70:71]
	s_add_i32 m0, s18, 0x1a000
	s_add_i32 s22, s18, 0x8000
	v_lshl_add_u64 v[10:11], s[6:7], 0, v[84:85]
	global_load_lds_dwordx4 v[2:3], off
	v_lshl_add_u64 v[2:3], v[8:9], 0, s[70:71]
	s_mov_b32 m0, s22
	s_add_i32 s23, s18, 0xa000
	v_lshl_add_u64 v[12:13], s[10:11], 0, v[0:1]
	global_load_lds_dwordx4 v[2:3], off
	v_lshl_add_u64 v[2:3], v[10:11], 0, s[70:71]
	s_mov_b32 m0, s23
	v_lshl_add_u64 v[14:15], s[10:11], 0, v[82:83]
	global_load_lds_dwordx4 v[2:3], off
	s_add_i32 m0, s18, 0x1c000
	v_lshl_add_u64 v[2:3], v[12:13], 0, s[70:71]
	global_load_lds_dwordx4 v[2:3], off
	v_lshl_add_u64 v[2:3], v[14:15], 0, s[70:71]
	s_add_i32 m0, s18, 0x1e000
	s_and_b32 s16, s13, 3
	global_load_lds_dwordx4 v[2:3], off
	s_waitcnt vmcnt(6)
	s_lshl_b32 s15, s12, 6
	v_mov_b32_e32 v145, 0
	s_cmp_lt_i32 s8, 64
	v_mov_b32_e32 v144, v145
	v_mov_b32_e32 v143, v145
	v_mov_b32_e32 v142, v145
	v_mov_b32_e32 v141, v145
	v_mov_b32_e32 v140, v145
	v_mov_b32_e32 v139, v145
	v_mov_b32_e32 v138, v145
	v_mov_b32_e32 v129, v145
	v_mov_b32_e32 v128, v145
	v_mov_b32_e32 v127, v145
	v_mov_b32_e32 v126, v145
	v_mov_b32_e32 v125, v145
	v_mov_b32_e32 v124, v145
	v_mov_b32_e32 v123, v145
	v_mov_b32_e32 v122, v145
	v_mov_b32_e32 v113, v145
	v_mov_b32_e32 v112, v145
	v_mov_b32_e32 v111, v145
	v_mov_b32_e32 v110, v145
	v_mov_b32_e32 v109, v145
	v_mov_b32_e32 v108, v145
	v_mov_b32_e32 v107, v145
	v_mov_b32_e32 v106, v145
	v_mov_b32_e32 v81, v145
	v_mov_b32_e32 v80, v145
	v_mov_b32_e32 v79, v145
	v_mov_b32_e32 v78, v145
	v_mov_b32_e32 v77, v145
	v_mov_b32_e32 v76, v145
	v_mov_b32_e32 v75, v145
	v_mov_b32_e32 v74, v145
	v_mov_b32_e32 v137, v145
	v_mov_b32_e32 v136, v145
	v_mov_b32_e32 v135, v145
	v_mov_b32_e32 v134, v145
	v_mov_b32_e32 v133, v145
	v_mov_b32_e32 v132, v145
	v_mov_b32_e32 v131, v145
	v_mov_b32_e32 v130, v145
	v_mov_b32_e32 v121, v145
	v_mov_b32_e32 v120, v145
	v_mov_b32_e32 v119, v145
	v_mov_b32_e32 v118, v145
	v_mov_b32_e32 v117, v145
	v_mov_b32_e32 v116, v145
	v_mov_b32_e32 v115, v145
	v_mov_b32_e32 v114, v145
	v_mov_b32_e32 v105, v145
	v_mov_b32_e32 v104, v145
	v_mov_b32_e32 v103, v145
	v_mov_b32_e32 v102, v145
	v_mov_b32_e32 v101, v145
	v_mov_b32_e32 v100, v145
	v_mov_b32_e32 v99, v145
	v_mov_b32_e32 v98, v145
	v_mov_b32_e32 v73, v145
	v_mov_b32_e32 v72, v145
	v_mov_b32_e32 v71, v145
	v_mov_b32_e32 v70, v145
	v_mov_b32_e32 v69, v145
	v_mov_b32_e32 v68, v145
	v_mov_b32_e32 v67, v145
	v_mov_b32_e32 v66, v145
	v_mov_b32_e32 v65, v145
	v_mov_b32_e32 v64, v145
	v_mov_b32_e32 v63, v145
	v_mov_b32_e32 v62, v145
	v_mov_b32_e32 v61, v145
	v_mov_b32_e32 v60, v145
	v_mov_b32_e32 v59, v145
	v_mov_b32_e32 v58, v145
	v_mov_b32_e32 v49, v145
	v_mov_b32_e32 v48, v145
	v_mov_b32_e32 v47, v145
	v_mov_b32_e32 v46, v145
	v_mov_b32_e32 v45, v145
	v_mov_b32_e32 v44, v145
	v_mov_b32_e32 v43, v145
	v_mov_b32_e32 v42, v145
	v_mov_b32_e32 v33, v145
	v_mov_b32_e32 v32, v145
	v_mov_b32_e32 v31, v145
	v_mov_b32_e32 v30, v145
	v_mov_b32_e32 v29, v145
	v_mov_b32_e32 v28, v145
	v_mov_b32_e32 v27, v145
	v_mov_b32_e32 v26, v145
	v_mov_b32_e32 v17, v145
	v_mov_b32_e32 v16, v145
	v_mov_b32_e32 v15, v145
	v_mov_b32_e32 v14, v145
	v_mov_b32_e32 v13, v145
	v_mov_b32_e32 v12, v145
	v_mov_b32_e32 v11, v145
	v_mov_b32_e32 v10, v145
	v_mov_b32_e32 v57, v145
	v_mov_b32_e32 v56, v145
	v_mov_b32_e32 v55, v145
	v_mov_b32_e32 v54, v145
	v_mov_b32_e32 v53, v145
	v_mov_b32_e32 v52, v145
	v_mov_b32_e32 v51, v145
	v_mov_b32_e32 v50, v145
	v_mov_b32_e32 v41, v145
	v_mov_b32_e32 v40, v145
	v_mov_b32_e32 v39, v145
	v_mov_b32_e32 v38, v145
	v_mov_b32_e32 v37, v145
	v_mov_b32_e32 v36, v145
	v_mov_b32_e32 v35, v145
	v_mov_b32_e32 v34, v145
	v_mov_b32_e32 v25, v145
	v_mov_b32_e32 v24, v145
	v_mov_b32_e32 v23, v145
	v_mov_b32_e32 v22, v145
	v_mov_b32_e32 v21, v145
	v_mov_b32_e32 v20, v145
	v_mov_b32_e32 v19, v145
	v_mov_b32_e32 v18, v145
	v_mov_b32_e32 v9, v145
	v_mov_b32_e32 v8, v145
	v_mov_b32_e32 v7, v145
	v_mov_b32_e32 v6, v145
	v_mov_b32_e32 v5, v145
	v_mov_b32_e32 v4, v145
	v_mov_b32_e32 v3, v145
	v_mov_b32_e32 v2, v145
	s_barrier
;   DI bool next(int i, Unit& o) const { if (i != 0 || !valid) return false; o = u; return true; }
; template <class Epi, class Sched>
; DI void gemm_phase(LAS unsigned char* lds, const Gemm g, const Sched& S, const Epi& E) {
;     ...
;     int R, C; stage_rc(tid * 16 + i * 8192, R, C);
;     int Rb = R;
;     if (Epi::BMAP == 1) Rb = (R & ~31) + perm32(R & 31);
;     if (Epi::BMAP == 2) Rb = 64 * (R >> 5) + perm32(R & 31);
;     voffA[i] = (unsigned)(R * K + C) * 2u; voffB[i] = (unsigned)(Rb * K + C) * 2u;
;   }
;   const size_t kstep = (size_t)(BK * 2);
;   const size_t hstep = (size_t)HALF * K * 2;
;   const size_t hstepB = (Epi::BMAP == 2) ? (size_t)32 * K * 2 : hstep;
;   const size_t tstep = 2 * hstep;
;   const unsigned ldsw = (unsigned)wid * 1024u;
;   const int aoff = lds_byte(wr * 64 + fr, fq * 8), boff = lds_byte(wc * 32 + fr, fq * 8);
;     ...
;   Unit cur, nxt; int ui = 0;
;   if (!S.next(0, cur)) return;
;   f32x4 acc[2][2][4][2];
; #pragma unroll
;   for (int a = 0; a < 2; ++a)
; #pragma unroll
;     for (int b = 0; b < 2; ++b)
; #pragma unroll
;       for (int m = 0; m < 4; ++m)
; #pragma unroll
;         for (int n = 0; n < 2; ++n) acc[a][b][m][n] = (f32x4){0.f, 0.f, 0.f, 0.f};
	s_cbranch_scc1 .LBB0_832
	s_lshr_b32 s9, s9, 26
	s_add_i32 s9, s8, s9
	v_or_b32_e32 v2, s15, v150
	s_ashr_i32 s24, s9, 6
	v_lshlrev_b32_e32 v3, 6, v2
	v_lshlrev_b32_e32 v4, 4, v148
	s_movk_i32 s9, 0x3c0
	v_lshlrev_b32_e32 v2, 2, v2
	v_and_or_b32 v3, v3, s9, v4
	s_lshl_b32 s9, s12, 13
	v_and_b32_e32 v2, 32, v2
	v_bitop3_b32 v5, v3, s9, v2 bitop3:0xde
	v_lshlrev_b32_e32 v3, 2, v150
	v_lshl_or_b32 v2, v150, 6, v4
	s_lshl_b32 s9, s16, 12
	v_and_b32_e32 v3, 32, v3
	v_readlane_b32 s10, v253, 35
	s_add_i32 s25, s24, -2
	v_bitop3_b32 v92, v2, s9, v3 bitop3:0xde
	s_mul_hi_i32 s9, s10, s8
	s_mul_i32 s8, s10, s8
	v_add_u32_e32 v2, v94, v88
	s_add_u32 s8, s86, s8
	v_add_lshl_u32 v2, v2, v89, 1
	v_mov_b32_e32 v3, v1
	s_addc_u32 s9, s87, s9
	v_lshl_add_u64 v[88:89], s[8:9], 0, v[2:3]
	v_add_u32_e32 v2, v93, v90
	v_add_lshl_u32 v2, v2, v91, 1
	v_lshl_add_u64 v[90:91], s[8:9], 0, v[2:3]
	v_mov_b32_e32 v2, 0
	s_mov_b32 s10, 0
	s_mov_b64 s[8:9], 0x2000080
	v_add_u32_e32 v93, 16, v5
	v_mov_b32_e32 v3, v2
	v_mov_b32_e32 v4, v2
	v_mov_b32_e32 v5, v2
	v_mov_b32_e32 v6, v2
	v_mov_b32_e32 v7, v2
	v_mov_b32_e32 v8, v2
	v_mov_b32_e32 v9, v2
	v_mov_b32_e32 v18, v2
	v_mov_b32_e32 v19, v2
	v_mov_b32_e32 v20, v2
	v_mov_b32_e32 v21, v2
	v_mov_b32_e32 v22, v2
	v_mov_b32_e32 v23, v2
	v_mov_b32_e32 v24, v2
	v_mov_b32_e32 v25, v2
	v_mov_b32_e32 v34, v2
	v_mov_b32_e32 v35, v2
	v_mov_b32_e32 v36, v2
	v_mov_b32_e32 v37, v2
	v_mov_b32_e32 v38, v2
	v_mov_b32_e32 v39, v2
	v_mov_b32_e32 v40, v2
	v_mov_b32_e32 v41, v2
	v_mov_b32_e32 v50, v2
	v_mov_b32_e32 v51, v2
	v_mov_b32_e32 v52, v2
	v_mov_b32_e32 v53, v2
	v_mov_b32_e32 v54, v2
	v_mov_b32_e32 v55, v2
	v_mov_b32_e32 v56, v2
	v_mov_b32_e32 v57, v2
	v_mov_b32_e32 v10, v2
	v_mov_b32_e32 v11, v2
	v_mov_b32_e32 v12, v2
	v_mov_b32_e32 v13, v2
	v_mov_b32_e32 v14, v2
	v_mov_b32_e32 v15, v2
	v_mov_b32_e32 v16, v2
	v_mov_b32_e32 v17, v2
	v_mov_b32_e32 v26, v2
	v_mov_b32_e32 v27, v2
	v_mov_b32_e32 v28, v2
	v_mov_b32_e32 v29, v2
	v_mov_b32_e32 v30, v2
	v_mov_b32_e32 v31, v2
	v_mov_b32_e32 v32, v2
	v_mov_b32_e32 v33, v2
	v_mov_b32_e32 v42, v2
	v_mov_b32_e32 v43, v2
	v_mov_b32_e32 v44, v2
	v_mov_b32_e32 v45, v2
	v_mov_b32_e32 v46, v2
	v_mov_b32_e32 v47, v2
	v_mov_b32_e32 v48, v2
	v_mov_b32_e32 v49, v2
	v_mov_b32_e32 v58, v2
	v_mov_b32_e32 v59, v2
	v_mov_b32_e32 v60, v2
	v_mov_b32_e32 v61, v2
	v_mov_b32_e32 v62, v2
	v_mov_b32_e32 v63, v2
	v_mov_b32_e32 v64, v2
	v_mov_b32_e32 v65, v2
	v_mov_b32_e32 v66, v2
	v_mov_b32_e32 v67, v2
	v_mov_b32_e32 v68, v2
	v_mov_b32_e32 v69, v2
	v_mov_b32_e32 v70, v2
	v_mov_b32_e32 v71, v2
	v_mov_b32_e32 v72, v2
	v_mov_b32_e32 v73, v2
	v_mov_b32_e32 v98, v2
	v_mov_b32_e32 v99, v2
	v_mov_b32_e32 v100, v2
	v_mov_b32_e32 v101, v2
	v_mov_b32_e32 v102, v2
	v_mov_b32_e32 v103, v2
	v_mov_b32_e32 v104, v2
	v_mov_b32_e32 v105, v2
	v_mov_b32_e32 v114, v2
	v_mov_b32_e32 v115, v2
	v_mov_b32_e32 v116, v2
	v_mov_b32_e32 v117, v2
	v_mov_b32_e32 v118, v2
	v_mov_b32_e32 v119, v2
	v_mov_b32_e32 v120, v2
	v_mov_b32_e32 v121, v2
	v_mov_b32_e32 v130, v2
	v_mov_b32_e32 v131, v2
	v_mov_b32_e32 v132, v2
	v_mov_b32_e32 v133, v2
	v_mov_b32_e32 v134, v2
	v_mov_b32_e32 v135, v2
	v_mov_b32_e32 v136, v2
	v_mov_b32_e32 v137, v2
	v_mov_b32_e32 v74, v2
	v_mov_b32_e32 v75, v2
	v_mov_b32_e32 v76, v2
	v_mov_b32_e32 v77, v2
	v_mov_b32_e32 v78, v2
	v_mov_b32_e32 v79, v2
	v_mov_b32_e32 v80, v2
	v_mov_b32_e32 v81, v2
	v_mov_b32_e32 v106, v2
	v_mov_b32_e32 v107, v2
	v_mov_b32_e32 v108, v2
	v_mov_b32_e32 v109, v2
	v_mov_b32_e32 v110, v2
	v_mov_b32_e32 v111, v2
	v_mov_b32_e32 v112, v2
	v_mov_b32_e32 v113, v2
	v_mov_b32_e32 v122, v2
	v_mov_b32_e32 v123, v2
	v_mov_b32_e32 v124, v2
	v_mov_b32_e32 v125, v2
	v_mov_b32_e32 v126, v2
	v_mov_b32_e32 v127, v2
	v_mov_b32_e32 v128, v2
	v_mov_b32_e32 v129, v2
	v_mov_b32_e32 v138, v2
	v_mov_b32_e32 v139, v2
	v_mov_b32_e32 v140, v2
	v_mov_b32_e32 v141, v2
	v_mov_b32_e32 v142, v2
	v_mov_b32_e32 v143, v2
	v_mov_b32_e32 v144, v2
	v_mov_b32_e32 v145, v2
	.p2align	6
